# H-scheme k-loops on 10 GEMM instances + batched out-phase epilogue loads + mla_q rope cos/sin prefetch ring + convT load hoisting
# speedup vs baseline: 1.0398x; 1.0398x over previous
.LBB0_21:
	s_ashr_i32 s6, s19, 31
	s_lshr_b32 s6, s6, 29
	s_add_i32 s6, s19, s6
	s_ashr_i32 s14, s6, 3
	s_lshl_b32 s22, s14, 6
	v_or_b32_e32 v0, s22, v14
	v_lshl_add_u32 v1, s14, 5, v15
	v_add_u32_e32 v2, 0xfffff800, v0
	v_cmp_gt_i32_e32 vcc, s18, v0
	s_mul_i32 s10, s14, 0xffa00000
	v_add_u32_e32 v6, s10, v23
	v_cndmask_b32_e32 v10, v2, v1, vcc
	v_cmp_lt_i32_e64 s[6:7], -1, v10
	v_lshl_add_u64 v[4:5], v[10:11], 2, s[42:43]
	v_mov_b32_e32 v10, v11
	v_mov_b64_e32 v[0:1], v[10:11]
	v_mov_b64_e32 v[2:3], v[10:11]
	s_waitcnt lgkmcnt(0)
	s_barrier
	s_and_saveexec_b64 s[10:11], s[6:7]
	s_cbranch_execz .LBB0_23
	v_ashrrev_i32_e32 v7, 31, v6
	v_lshl_add_u64 v[0:1], v[6:7], 2, v[4:5]
	global_load_dwordx4 v[0:3], v[0:1], off
	v_add_u32_e32 v56, 0x30000, v6
	v_ashrrev_i32_e32 v57, 31, v56
	v_lshl_add_u64 v[56:57], v[56:57], 2, v[4:5]
	global_load_dwordx4 v[40:43], v[56:57], off
	v_add_u32_e32 v56, 0x60000, v6
	v_ashrrev_i32_e32 v57, 31, v56
	v_lshl_add_u64 v[56:57], v[56:57], 2, v[4:5]
	global_load_dwordx4 v[44:47], v[56:57], off
	v_add_u32_e32 v56, 0x90000, v6
	v_ashrrev_i32_e32 v57, 31, v56
	v_lshl_add_u64 v[56:57], v[56:57], 2, v[4:5]
	global_load_dwordx4 v[48:51], v[56:57], off
.LBB0_23:
	s_or_b64 exec, exec, s[10:11]
	s_lshl_b32 s10, s14, 10
	s_and_b64 vcc, exec, s[4:5]
	s_sub_i32 s14, 0, s10
	s_cbranch_vccnz .LBB0_25
	s_add_i32 s10, s14, s3
	v_add_u32_e32 v24, s10, v8
	v_ashrrev_i32_e32 v25, 31, v24
	v_lshl_add_u64 v[24:25], v[24:25], 2, s[40:41]
	global_load_dword v10, v[24:25], off
	global_load_dword v52, v[24:25], off offset:128
	global_load_dword v53, v[24:25], off offset:256
	global_load_dword v54, v[24:25], off offset:384
	s_waitcnt vmcnt(0)
	v_pk_mul_f32 v[0:1], v[0:1], v[10:11] op_sel_hi:[1,0]
	v_pk_mul_f32 v[2:3], v[2:3], v[10:11] op_sel_hi:[1,0]
.LBB0_25:
	v_mov_b32_e32 v10, v11
	s_waitcnt vmcnt(0)
	ds_write_b128 v17, v[0:3]
	v_mov_b64_e32 v[0:1], v[10:11]
	v_mov_b64_e32 v[2:3], v[10:11]
	s_and_saveexec_b64 s[10:11], s[6:7]
	s_cbranch_execz .LBB0_27
	v_mov_b64_e32 v[0:1], v[40:41]
	v_mov_b64_e32 v[2:3], v[42:43]
.LBB0_27:
	s_or_b64 exec, exec, s[10:11]
	s_and_b64 vcc, exec, s[4:5]
	s_add_i32 s10, s3, s14
	s_cbranch_vccnz .LBB0_29
	s_ashr_i32 s11, s10, 31
	v_lshl_add_u64 v[24:25], s[10:11], 0, v[8:9]
	v_lshl_add_u64 v[24:25], v[24:25], 2, s[40:41]
	v_mov_b32_e32 v10, v52
	s_waitcnt vmcnt(0)
	v_pk_mul_f32 v[0:1], v[0:1], v[10:11] op_sel_hi:[1,0]
	v_pk_mul_f32 v[2:3], v[2:3], v[10:11] op_sel_hi:[1,0]
.LBB0_29:
	v_mov_b32_e32 v10, v11
	s_waitcnt vmcnt(0)
	ds_write_b128 v19, v[0:3]
	v_mov_b64_e32 v[0:1], v[10:11]
	v_mov_b64_e32 v[2:3], v[10:11]
	s_and_saveexec_b64 s[14:15], s[6:7]
	s_cbranch_execz .LBB0_31
	v_mov_b64_e32 v[0:1], v[44:45]
	v_mov_b64_e32 v[2:3], v[46:47]
.LBB0_31:
	s_or_b64 exec, exec, s[14:15]
	s_and_b64 vcc, exec, s[4:5]
	s_cbranch_vccnz .LBB0_33
	s_ashr_i32 s11, s10, 31
	v_lshl_add_u64 v[24:25], s[10:11], 0, v[8:9]
	v_lshl_add_u64 v[24:25], v[24:25], 2, s[40:41]
	v_mov_b32_e32 v10, v53
	s_waitcnt vmcnt(0)
	v_pk_mul_f32 v[0:1], v[0:1], v[10:11] op_sel_hi:[1,0]
	v_pk_mul_f32 v[2:3], v[2:3], v[10:11] op_sel_hi:[1,0]
.LBB0_33:
	v_mov_b32_e32 v10, v11
	s_waitcnt vmcnt(0)
	ds_write_b128 v20, v[0:3]
	v_mov_b64_e32 v[0:1], v[10:11]
	v_mov_b64_e32 v[2:3], v[10:11]
	s_and_saveexec_b64 s[14:15], s[6:7]
	s_cbranch_execz .LBB0_35
	v_mov_b64_e32 v[0:1], v[48:49]
	v_mov_b64_e32 v[2:3], v[50:51]
.LBB0_35:
	s_or_b64 exec, exec, s[14:15]
	s_and_b64 vcc, exec, s[8:9]
	s_cbranch_vccz .LBB0_37
	s_ashr_i32 s11, s10, 31
	v_lshl_add_u64 v[4:5], s[10:11], 0, v[8:9]
	v_lshl_add_u64 v[4:5], v[4:5], 2, s[40:41]
	v_mov_b32_e32 v6, v54
	s_waitcnt vmcnt(0)
	v_pk_mul_f32 v[4:5], v[0:1], v[6:7] op_sel_hi:[1,0]
	v_pk_mul_f32 v[6:7], v[2:3], v[6:7] op_sel_hi:[1,0]
	s_cbranch_execnz .LBB0_20
	s_branch .LBB0_38

.LBB0_262:
	v_lshl_add_u32 v132, s48, 8, v134
	s_lshl_b32 s6, s6, 8
	v_ashrrev_i32_e32 v133, 31, v132
	v_lshl_add_u64 v[130:131], v[128:129], 0, s[6:7]
	v_lshlrev_b64 v[136:137], 10, v[132:133]
	v_lshl_add_u64 v[136:137], v[136:137], 0, v[130:131]
	v_lshlrev_b64 v[136:137], 2, v[136:137]
	s_add_i32 s58, s58, s82
	s_add_i32 s57, s57, s82
	s_mov_b32 s50, s36
	s_mov_b32 s51, s37
	s_mov_b32 s52, s78
	s_mov_b32 s53, s79
	global_load_dword v140, v136, s[50:51]
	global_load_dword v141, v136, s[50:51] offset:64
	global_load_dword v142, v136, s[50:51] offset:128
	global_load_dword v143, v136, s[50:51] offset:192
	s_add_u32 s50, s50, 0x1000
	s_addc_u32 s51, s51, 0
	global_load_dword v144, v136, s[50:51]
	global_load_dword v145, v136, s[50:51] offset:64
	global_load_dword v146, v136, s[50:51] offset:128
	global_load_dword v147, v136, s[50:51] offset:192
	s_add_u32 s50, s50, 0x1000
	s_addc_u32 s51, s51, 0
	global_load_dword v148, v136, s[50:51]
	global_load_dword v149, v136, s[50:51] offset:64
	global_load_dword v150, v136, s[50:51] offset:128
	global_load_dword v151, v136, s[50:51] offset:192
	s_add_u32 s50, s50, 0x1000
	s_addc_u32 s51, s51, 0
	global_load_dword v152, v136, s[50:51]
	global_load_dword v153, v136, s[50:51] offset:64
	global_load_dword v154, v136, s[50:51] offset:128
	global_load_dword v155, v136, s[50:51] offset:192
	s_add_u32 s50, s50, 0xd000
	s_addc_u32 s51, s51, 0
	global_load_dword v156, v136, s[50:51]
	global_load_dword v157, v136, s[50:51] offset:64
	global_load_dword v158, v136, s[50:51] offset:128
	global_load_dword v159, v136, s[50:51] offset:192
	s_add_u32 s50, s50, 0x1000
	s_addc_u32 s51, s51, 0
	global_load_dword v160, v136, s[50:51]
	global_load_dword v161, v136, s[50:51] offset:64
	global_load_dword v162, v136, s[50:51] offset:128
	global_load_dword v163, v136, s[50:51] offset:192
	s_add_u32 s50, s50, 0x1000
	s_addc_u32 s51, s51, 0
	global_load_dword v164, v136, s[50:51]
	global_load_dword v165, v136, s[50:51] offset:64
	global_load_dword v166, v136, s[50:51] offset:128
	global_load_dword v167, v136, s[50:51] offset:192
	s_add_u32 s50, s50, 0x1000
	s_addc_u32 s51, s51, 0
	global_load_dword v168, v136, s[50:51]
	global_load_dword v169, v136, s[50:51] offset:64
	global_load_dword v170, v136, s[50:51] offset:128
	global_load_dword v171, v136, s[50:51] offset:192
	s_waitcnt vmcnt(16)
	v_add_f32_e32 v124, v124, v140
	global_store_dword v136, v124, s[52:53]
	v_add_f32_e32 v120, v120, v141
	global_store_dword v136, v120, s[52:53] offset:64
	v_add_f32_e32 v116, v116, v142
	global_store_dword v136, v116, s[52:53] offset:128
	v_add_f32_e32 v112, v112, v143
	global_store_dword v136, v112, s[52:53] offset:192
	s_add_u32 s52, s52, 0x1000
	s_addc_u32 s53, s53, 0
	v_add_f32_e32 v125, v125, v144
	global_store_dword v136, v125, s[52:53]
	v_add_f32_e32 v121, v121, v145
	global_store_dword v136, v121, s[52:53] offset:64
	v_add_f32_e32 v117, v117, v146
	global_store_dword v136, v117, s[52:53] offset:128
	v_add_f32_e32 v113, v113, v147
	global_store_dword v136, v113, s[52:53] offset:192
	s_add_u32 s52, s52, 0x1000
	s_addc_u32 s53, s53, 0
	v_add_f32_e32 v126, v126, v148
	global_store_dword v136, v126, s[52:53]
	v_add_f32_e32 v122, v122, v149
	global_store_dword v136, v122, s[52:53] offset:64
	v_add_f32_e32 v118, v118, v150
	global_store_dword v136, v118, s[52:53] offset:128
	v_add_f32_e32 v114, v114, v151
	global_store_dword v136, v114, s[52:53] offset:192
	s_add_u32 s52, s52, 0x1000
	s_addc_u32 s53, s53, 0
	v_add_f32_e32 v127, v127, v152
	global_store_dword v136, v127, s[52:53]
	v_add_f32_e32 v123, v123, v153
	global_store_dword v136, v123, s[52:53] offset:64
	v_add_f32_e32 v119, v119, v154
	global_store_dword v136, v119, s[52:53] offset:128
	v_add_f32_e32 v115, v115, v155
	global_store_dword v136, v115, s[52:53] offset:192
	s_waitcnt vmcnt(47)
	s_add_u32 s50, s50, 0xd000
	s_addc_u32 s51, s51, 0
	global_load_dword v140, v136, s[50:51]
	global_load_dword v141, v136, s[50:51] offset:64
	global_load_dword v142, v136, s[50:51] offset:128
	global_load_dword v143, v136, s[50:51] offset:192
	s_add_u32 s50, s50, 0x1000
	s_addc_u32 s51, s51, 0
	global_load_dword v144, v136, s[50:51]
	global_load_dword v145, v136, s[50:51] offset:64
	global_load_dword v146, v136, s[50:51] offset:128
	global_load_dword v147, v136, s[50:51] offset:192
	s_add_u32 s50, s50, 0x1000
	s_addc_u32 s51, s51, 0
	global_load_dword v148, v136, s[50:51]
	global_load_dword v149, v136, s[50:51] offset:64
	global_load_dword v150, v136, s[50:51] offset:128
	global_load_dword v151, v136, s[50:51] offset:192
	s_add_u32 s50, s50, 0x1000
	s_addc_u32 s51, s51, 0
	global_load_dword v152, v136, s[50:51]
	global_load_dword v153, v136, s[50:51] offset:64
	global_load_dword v154, v136, s[50:51] offset:128
	global_load_dword v155, v136, s[50:51] offset:192
	s_waitcnt vmcnt(32)
	s_add_u32 s52, s52, 0xd000
	s_addc_u32 s53, s53, 0
	v_add_f32_e32 v108, v108, v156
	global_store_dword v136, v108, s[52:53]
	v_add_f32_e32 v104, v104, v157
	global_store_dword v136, v104, s[52:53] offset:64
	v_add_f32_e32 v100, v100, v158
	global_store_dword v136, v100, s[52:53] offset:128
	v_add_f32_e32 v96, v96, v159
	global_store_dword v136, v96, s[52:53] offset:192
	s_add_u32 s52, s52, 0x1000
	s_addc_u32 s53, s53, 0
	v_add_f32_e32 v109, v109, v160
	global_store_dword v136, v109, s[52:53]
	v_add_f32_e32 v105, v105, v161
	global_store_dword v136, v105, s[52:53] offset:64
	v_add_f32_e32 v101, v101, v162
	global_store_dword v136, v101, s[52:53] offset:128
	v_add_f32_e32 v97, v97, v163
	global_store_dword v136, v97, s[52:53] offset:192
	s_add_u32 s52, s52, 0x1000
	s_addc_u32 s53, s53, 0
	v_add_f32_e32 v110, v110, v164
	global_store_dword v136, v110, s[52:53]
	v_add_f32_e32 v106, v106, v165
	global_store_dword v136, v106, s[52:53] offset:64
	v_add_f32_e32 v102, v102, v166
	global_store_dword v136, v102, s[52:53] offset:128
	v_add_f32_e32 v98, v98, v167
	global_store_dword v136, v98, s[52:53] offset:192
	s_add_u32 s52, s52, 0x1000
	s_addc_u32 s53, s53, 0
	v_add_f32_e32 v111, v111, v168
	global_store_dword v136, v111, s[52:53]
	v_add_f32_e32 v107, v107, v169
	global_store_dword v136, v107, s[52:53] offset:64
	v_add_f32_e32 v103, v103, v170
	global_store_dword v136, v103, s[52:53] offset:128
	v_add_f32_e32 v99, v99, v171
	global_store_dword v136, v99, s[52:53] offset:192
	s_waitcnt vmcnt(47)
	s_add_u32 s50, s50, 0xd000
	s_addc_u32 s51, s51, 0
	global_load_dword v156, v136, s[50:51]
	global_load_dword v157, v136, s[50:51] offset:64
	global_load_dword v158, v136, s[50:51] offset:128
	global_load_dword v159, v136, s[50:51] offset:192
	s_add_u32 s50, s50, 0x1000
	s_addc_u32 s51, s51, 0
	global_load_dword v160, v136, s[50:51]
	global_load_dword v161, v136, s[50:51] offset:64
	global_load_dword v162, v136, s[50:51] offset:128
	global_load_dword v163, v136, s[50:51] offset:192
	s_add_u32 s50, s50, 0x1000
	s_addc_u32 s51, s51, 0
	global_load_dword v164, v136, s[50:51]
	global_load_dword v165, v136, s[50:51] offset:64
	global_load_dword v166, v136, s[50:51] offset:128
	global_load_dword v167, v136, s[50:51] offset:192
	s_add_u32 s50, s50, 0x1000
	s_addc_u32 s51, s51, 0
	global_load_dword v168, v136, s[50:51]
	global_load_dword v169, v136, s[50:51] offset:64
	global_load_dword v170, v136, s[50:51] offset:128
	global_load_dword v171, v136, s[50:51] offset:192
	s_waitcnt vmcnt(32)
	s_add_u32 s52, s52, 0xd000
	s_addc_u32 s53, s53, 0
	v_add_f32_e32 v92, v92, v140
	global_store_dword v136, v92, s[52:53]
	v_add_f32_e32 v88, v88, v141
	global_store_dword v136, v88, s[52:53] offset:64
	v_add_f32_e32 v84, v84, v142
	global_store_dword v136, v84, s[52:53] offset:128
	v_add_f32_e32 v80, v80, v143
	global_store_dword v136, v80, s[52:53] offset:192
	s_add_u32 s52, s52, 0x1000
	s_addc_u32 s53, s53, 0
	v_add_f32_e32 v93, v93, v144
	global_store_dword v136, v93, s[52:53]
	v_add_f32_e32 v89, v89, v145
	global_store_dword v136, v89, s[52:53] offset:64
	v_add_f32_e32 v85, v85, v146
	global_store_dword v136, v85, s[52:53] offset:128
	v_add_f32_e32 v81, v81, v147
	global_store_dword v136, v81, s[52:53] offset:192
	s_add_u32 s52, s52, 0x1000
	s_addc_u32 s53, s53, 0
	v_add_f32_e32 v94, v94, v148
	global_store_dword v136, v94, s[52:53]
	v_add_f32_e32 v90, v90, v149
	global_store_dword v136, v90, s[52:53] offset:64
	v_add_f32_e32 v86, v86, v150
	global_store_dword v136, v86, s[52:53] offset:128
	v_add_f32_e32 v82, v82, v151
	global_store_dword v136, v82, s[52:53] offset:192
	s_add_u32 s52, s52, 0x1000
	s_addc_u32 s53, s53, 0
	v_add_f32_e32 v95, v95, v152
	global_store_dword v136, v95, s[52:53]
	v_add_f32_e32 v91, v91, v153
	global_store_dword v136, v91, s[52:53] offset:64
	v_add_f32_e32 v87, v87, v154
	global_store_dword v136, v87, s[52:53] offset:128
	v_add_f32_e32 v83, v83, v155
	global_store_dword v136, v83, s[52:53] offset:192
	s_waitcnt vmcnt(47)
	s_add_u32 s50, s50, 0xd000
	s_addc_u32 s51, s51, 0
	global_load_dword v140, v136, s[50:51]
	global_load_dword v141, v136, s[50:51] offset:64
	global_load_dword v142, v136, s[50:51] offset:128
	global_load_dword v143, v136, s[50:51] offset:192
	s_add_u32 s50, s50, 0x1000
	s_addc_u32 s51, s51, 0
	global_load_dword v144, v136, s[50:51]
	global_load_dword v145, v136, s[50:51] offset:64
	global_load_dword v146, v136, s[50:51] offset:128
	global_load_dword v147, v136, s[50:51] offset:192
	s_add_u32 s50, s50, 0x1000
	s_addc_u32 s51, s51, 0
	global_load_dword v148, v136, s[50:51]
	global_load_dword v149, v136, s[50:51] offset:64
	global_load_dword v150, v136, s[50:51] offset:128
	global_load_dword v151, v136, s[50:51] offset:192
	s_add_u32 s50, s50, 0x1000
	s_addc_u32 s51, s51, 0
	global_load_dword v152, v136, s[50:51]
	global_load_dword v153, v136, s[50:51] offset:64
	global_load_dword v154, v136, s[50:51] offset:128
	global_load_dword v155, v136, s[50:51] offset:192
	s_waitcnt vmcnt(32)
	s_add_u32 s52, s52, 0xd000
	s_addc_u32 s53, s53, 0
	v_add_f32_e32 v76, v76, v156
	global_store_dword v136, v76, s[52:53]
	v_add_f32_e32 v72, v72, v157
	global_store_dword v136, v72, s[52:53] offset:64
	v_add_f32_e32 v68, v68, v158
	global_store_dword v136, v68, s[52:53] offset:128
	v_add_f32_e32 v64, v64, v159
	global_store_dword v136, v64, s[52:53] offset:192
	s_add_u32 s52, s52, 0x1000
	s_addc_u32 s53, s53, 0
	v_add_f32_e32 v77, v77, v160
	global_store_dword v136, v77, s[52:53]
	v_add_f32_e32 v73, v73, v161
	global_store_dword v136, v73, s[52:53] offset:64
	v_add_f32_e32 v69, v69, v162
	global_store_dword v136, v69, s[52:53] offset:128
	v_add_f32_e32 v65, v65, v163
	global_store_dword v136, v65, s[52:53] offset:192
	s_add_u32 s52, s52, 0x1000
	s_addc_u32 s53, s53, 0
	v_add_f32_e32 v78, v78, v164
	global_store_dword v136, v78, s[52:53]
	v_add_f32_e32 v74, v74, v165
	global_store_dword v136, v74, s[52:53] offset:64
	v_add_f32_e32 v70, v70, v166
	global_store_dword v136, v70, s[52:53] offset:128
	v_add_f32_e32 v66, v66, v167
	global_store_dword v136, v66, s[52:53] offset:192
	s_add_u32 s52, s52, 0x1000
	s_addc_u32 s53, s53, 0
	v_add_f32_e32 v79, v79, v168
	global_store_dword v136, v79, s[52:53]
	v_add_f32_e32 v75, v75, v169
	global_store_dword v136, v75, s[52:53] offset:64
	v_add_f32_e32 v71, v71, v170
	global_store_dword v136, v71, s[52:53] offset:128
	v_add_f32_e32 v67, v67, v171
	global_store_dword v136, v67, s[52:53] offset:192
	s_waitcnt vmcnt(47)
	s_add_u32 s50, s50, 0xd000
	s_addc_u32 s51, s51, 0
	global_load_dword v156, v136, s[50:51]
	global_load_dword v157, v136, s[50:51] offset:64
	global_load_dword v158, v136, s[50:51] offset:128
	global_load_dword v159, v136, s[50:51] offset:192
	s_add_u32 s50, s50, 0x1000
	s_addc_u32 s51, s51, 0
	global_load_dword v160, v136, s[50:51]
	global_load_dword v161, v136, s[50:51] offset:64
	global_load_dword v162, v136, s[50:51] offset:128
	global_load_dword v163, v136, s[50:51] offset:192
	s_add_u32 s50, s50, 0x1000
	s_addc_u32 s51, s51, 0
	global_load_dword v164, v136, s[50:51]
	global_load_dword v165, v136, s[50:51] offset:64
	global_load_dword v166, v136, s[50:51] offset:128
	global_load_dword v167, v136, s[50:51] offset:192
	s_add_u32 s50, s50, 0x1000
	s_addc_u32 s51, s51, 0
	global_load_dword v168, v136, s[50:51]
	global_load_dword v169, v136, s[50:51] offset:64
	global_load_dword v170, v136, s[50:51] offset:128
	global_load_dword v171, v136, s[50:51] offset:192
	s_waitcnt vmcnt(32)
	s_add_u32 s52, s52, 0xd000
	s_addc_u32 s53, s53, 0
	v_add_f32_e32 v60, v60, v140
	global_store_dword v136, v60, s[52:53]
	v_add_f32_e32 v56, v56, v141
	global_store_dword v136, v56, s[52:53] offset:64
	v_add_f32_e32 v52, v52, v142
	global_store_dword v136, v52, s[52:53] offset:128
	v_add_f32_e32 v48, v48, v143
	global_store_dword v136, v48, s[52:53] offset:192
	s_add_u32 s52, s52, 0x1000
	s_addc_u32 s53, s53, 0
	v_add_f32_e32 v61, v61, v144
	global_store_dword v136, v61, s[52:53]
	v_add_f32_e32 v57, v57, v145
	global_store_dword v136, v57, s[52:53] offset:64
	v_add_f32_e32 v53, v53, v146
	global_store_dword v136, v53, s[52:53] offset:128
	v_add_f32_e32 v49, v49, v147
	global_store_dword v136, v49, s[52:53] offset:192
	s_add_u32 s52, s52, 0x1000
	s_addc_u32 s53, s53, 0
	v_add_f32_e32 v62, v62, v148
	global_store_dword v136, v62, s[52:53]
	v_add_f32_e32 v58, v58, v149
	global_store_dword v136, v58, s[52:53] offset:64
	v_add_f32_e32 v54, v54, v150
	global_store_dword v136, v54, s[52:53] offset:128
	v_add_f32_e32 v50, v50, v151
	global_store_dword v136, v50, s[52:53] offset:192
	s_add_u32 s52, s52, 0x1000
	s_addc_u32 s53, s53, 0
	v_add_f32_e32 v63, v63, v152
	global_store_dword v136, v63, s[52:53]
	v_add_f32_e32 v59, v59, v153
	global_store_dword v136, v59, s[52:53] offset:64
	v_add_f32_e32 v55, v55, v154
	global_store_dword v136, v55, s[52:53] offset:128
	v_add_f32_e32 v51, v51, v155
	global_store_dword v136, v51, s[52:53] offset:192
	s_waitcnt vmcnt(47)
	s_add_u32 s50, s50, 0xd000
	s_addc_u32 s51, s51, 0
	global_load_dword v140, v136, s[50:51]
	global_load_dword v141, v136, s[50:51] offset:64
	global_load_dword v142, v136, s[50:51] offset:128
	global_load_dword v143, v136, s[50:51] offset:192
	s_add_u32 s50, s50, 0x1000
	s_addc_u32 s51, s51, 0
	global_load_dword v144, v136, s[50:51]
	global_load_dword v145, v136, s[50:51] offset:64
	global_load_dword v146, v136, s[50:51] offset:128
	global_load_dword v147, v136, s[50:51] offset:192
	s_add_u32 s50, s50, 0x1000
	s_addc_u32 s51, s51, 0
	global_load_dword v148, v136, s[50:51]
	global_load_dword v149, v136, s[50:51] offset:64
	global_load_dword v150, v136, s[50:51] offset:128
	global_load_dword v151, v136, s[50:51] offset:192
	s_add_u32 s50, s50, 0x1000
	s_addc_u32 s51, s51, 0
	global_load_dword v152, v136, s[50:51]
	global_load_dword v153, v136, s[50:51] offset:64
	global_load_dword v154, v136, s[50:51] offset:128
	global_load_dword v155, v136, s[50:51] offset:192
	s_waitcnt vmcnt(32)
	s_add_u32 s52, s52, 0xd000
	s_addc_u32 s53, s53, 0
	v_add_f32_e32 v44, v44, v156
	global_store_dword v136, v44, s[52:53]
	v_add_f32_e32 v40, v40, v157
	global_store_dword v136, v40, s[52:53] offset:64
	v_add_f32_e32 v36, v36, v158
	global_store_dword v136, v36, s[52:53] offset:128
	v_add_f32_e32 v32, v32, v159
	global_store_dword v136, v32, s[52:53] offset:192
	s_add_u32 s52, s52, 0x1000
	s_addc_u32 s53, s53, 0
	v_add_f32_e32 v45, v45, v160
	global_store_dword v136, v45, s[52:53]
	v_add_f32_e32 v41, v41, v161
	global_store_dword v136, v41, s[52:53] offset:64
	v_add_f32_e32 v37, v37, v162
	global_store_dword v136, v37, s[52:53] offset:128
	v_add_f32_e32 v33, v33, v163
	global_store_dword v136, v33, s[52:53] offset:192
	s_add_u32 s52, s52, 0x1000
	s_addc_u32 s53, s53, 0
	v_add_f32_e32 v46, v46, v164
	global_store_dword v136, v46, s[52:53]
	v_add_f32_e32 v42, v42, v165
	global_store_dword v136, v42, s[52:53] offset:64
	v_add_f32_e32 v38, v38, v166
	global_store_dword v136, v38, s[52:53] offset:128
	v_add_f32_e32 v34, v34, v167
	global_store_dword v136, v34, s[52:53] offset:192
	s_add_u32 s52, s52, 0x1000
	s_addc_u32 s53, s53, 0
	v_add_f32_e32 v47, v47, v168
	global_store_dword v136, v47, s[52:53]
	v_add_f32_e32 v43, v43, v169
	global_store_dword v136, v43, s[52:53] offset:64
	v_add_f32_e32 v39, v39, v170
	global_store_dword v136, v39, s[52:53] offset:128
	v_add_f32_e32 v35, v35, v171
	global_store_dword v136, v35, s[52:53] offset:192
	s_waitcnt vmcnt(47)
	s_add_u32 s50, s50, 0xd000
	s_addc_u32 s51, s51, 0
	global_load_dword v156, v136, s[50:51]
	global_load_dword v157, v136, s[50:51] offset:64
	global_load_dword v158, v136, s[50:51] offset:128
	global_load_dword v159, v136, s[50:51] offset:192
	s_add_u32 s50, s50, 0x1000
	s_addc_u32 s51, s51, 0
	global_load_dword v160, v136, s[50:51]
	global_load_dword v161, v136, s[50:51] offset:64
	global_load_dword v162, v136, s[50:51] offset:128
	global_load_dword v163, v136, s[50:51] offset:192
	s_add_u32 s50, s50, 0x1000
	s_addc_u32 s51, s51, 0
	global_load_dword v164, v136, s[50:51]
	global_load_dword v165, v136, s[50:51] offset:64
	global_load_dword v166, v136, s[50:51] offset:128
	global_load_dword v167, v136, s[50:51] offset:192
	s_add_u32 s50, s50, 0x1000
	s_addc_u32 s51, s51, 0
	global_load_dword v168, v136, s[50:51]
	global_load_dword v169, v136, s[50:51] offset:64
	global_load_dword v170, v136, s[50:51] offset:128
	global_load_dword v171, v136, s[50:51] offset:192
	s_waitcnt vmcnt(32)
	s_add_u32 s52, s52, 0xd000
	s_addc_u32 s53, s53, 0
	v_add_f32_e32 v28, v28, v140
	global_store_dword v136, v28, s[52:53]
	v_add_f32_e32 v20, v20, v141
	global_store_dword v136, v20, s[52:53] offset:64
	v_add_f32_e32 v16, v16, v142
	global_store_dword v136, v16, s[52:53] offset:128
	v_add_f32_e32 v8, v8, v143
	global_store_dword v136, v8, s[52:53] offset:192
	s_add_u32 s52, s52, 0x1000
	s_addc_u32 s53, s53, 0
	v_add_f32_e32 v29, v29, v144
	global_store_dword v136, v29, s[52:53]
	v_add_f32_e32 v21, v21, v145
	global_store_dword v136, v21, s[52:53] offset:64
	v_add_f32_e32 v17, v17, v146
	global_store_dword v136, v17, s[52:53] offset:128
	v_add_f32_e32 v9, v9, v147
	global_store_dword v136, v9, s[52:53] offset:192
	s_add_u32 s52, s52, 0x1000
	s_addc_u32 s53, s53, 0
	v_add_f32_e32 v30, v30, v148
	global_store_dword v136, v30, s[52:53]
	v_add_f32_e32 v22, v22, v149
	global_store_dword v136, v22, s[52:53] offset:64
	v_add_f32_e32 v18, v18, v150
	global_store_dword v136, v18, s[52:53] offset:128
	v_add_f32_e32 v10, v10, v151
	global_store_dword v136, v10, s[52:53] offset:192
	s_add_u32 s52, s52, 0x1000
	s_addc_u32 s53, s53, 0
	v_add_f32_e32 v31, v31, v152
	global_store_dword v136, v31, s[52:53]
	v_add_f32_e32 v23, v23, v153
	global_store_dword v136, v23, s[52:53] offset:64
	v_add_f32_e32 v19, v19, v154
	global_store_dword v136, v19, s[52:53] offset:128
	v_add_f32_e32 v11, v11, v155
	global_store_dword v136, v11, s[52:53] offset:192
	s_waitcnt vmcnt(16)
	s_add_u32 s52, s52, 0xd000
	s_addc_u32 s53, s53, 0
	v_add_f32_e32 v4, v4, v156
	global_store_dword v136, v4, s[52:53]
	v_add_f32_e32 v0, v0, v157
	global_store_dword v136, v0, s[52:53] offset:64
	v_add_f32_e32 v24, v24, v158
	global_store_dword v136, v24, s[52:53] offset:128
	v_add_f32_e32 v12, v12, v159
	global_store_dword v136, v12, s[52:53] offset:192
	s_add_u32 s52, s52, 0x1000
	s_addc_u32 s53, s53, 0
	v_add_f32_e32 v5, v5, v160
	global_store_dword v136, v5, s[52:53]
	v_add_f32_e32 v1, v1, v161
	global_store_dword v136, v1, s[52:53] offset:64
	v_add_f32_e32 v25, v25, v162
	global_store_dword v136, v25, s[52:53] offset:128
	v_add_f32_e32 v13, v13, v163
	global_store_dword v136, v13, s[52:53] offset:192
	s_add_u32 s52, s52, 0x1000
	s_addc_u32 s53, s53, 0
	v_add_f32_e32 v6, v6, v164
	global_store_dword v136, v6, s[52:53]
	v_add_f32_e32 v2, v2, v165
	global_store_dword v136, v2, s[52:53] offset:64
	v_add_f32_e32 v26, v26, v166
	global_store_dword v136, v26, s[52:53] offset:128
	v_add_f32_e32 v14, v14, v167
	global_store_dword v136, v14, s[52:53] offset:192
	s_add_u32 s52, s52, 0x1000
	s_addc_u32 s53, s53, 0
	v_add_f32_e32 v7, v7, v168
	global_store_dword v136, v7, s[52:53]
	v_add_f32_e32 v3, v3, v169
	global_store_dword v136, v3, s[52:53] offset:64
	v_add_f32_e32 v27, v27, v170
	global_store_dword v136, v27, s[52:53] offset:128
	v_add_f32_e32 v15, v15, v171
	global_store_dword v136, v15, s[52:53] offset:192
	s_cmpk_lt_i32 s58, 0x100
	s_cbranch_scc0 .LBB0_269

.LBB0_660:
	s_ashr_i32 s96, s94, 3
	s_and_b32 s21, s94, 7
	s_and_b32 s70, s96, -8
	s_or_b32 s64, s70, s21
	s_lshl_b32 s20, s91, 11
	s_ashr_i32 s65, s64, 31
	v_mov_b32_e32 v6, v181
	s_and_b32 s97, s93, 7
	s_bfe_u32 s6, s91, 0x30008
	s_and_b32 s20, s20, 0x380000
	s_lshl_b64 s[66:67], s[64:65], 19
	s_add_u32 s66, s3, s66
	v_lshrrev_b32_e32 v7, 4, v6
	v_lshlrev_b32_e32 v1, 6, v6
	v_xor_b32_e32 v0, v7, v6
	v_and_b32_e32 v8, 0x3c0, v1
	v_lshlrev_b32_e32 v1, 7, v6
	s_addc_u32 s67, s72, s67
	s_lshl_b32 s21, s94, 5
	v_lshlrev_b32_e32 v0, 3, v0
	v_and_b32_e32 v1, 0xfffffc00, v1
	s_and_b32 s95, s21, 0x700
	v_and_or_b32 v0, v0, 56, v1
	s_lshl_b32 s21, s95, 11
	v_ashrrev_i32_e32 v1, 31, v0
	v_lshl_add_u32 v142, v6, 4, 0
	s_add_u32 s68, s73, s21
	v_lshlrev_b64 v[0:1], 1, v[0:1]
	v_readfirstlane_b32 s21, v142
	v_add_u32_e32 v9, 0x2000, v142
	v_lshl_add_u64 v[2:3], s[66:67], 0, v[0:1]
	s_mov_b32 m0, s21
	v_readfirstlane_b32 s21, v9
	v_add_u32_e32 v9, 0x4000, v142
	s_waitcnt vmcnt(63) expcnt(7) lgkmcnt(15)
	s_barrier
	global_load_lds_dwordx4 v[2:3], off
	v_lshl_add_u64 v[4:5], v[2:3], 0, s[8:9]
	s_mov_b32 m0, s21
	v_readfirstlane_b32 s21, v9
	global_load_lds_dwordx4 v[4:5], off
	v_lshl_add_u64 v[4:5], v[2:3], 0, s[10:11]
	s_mov_b32 m0, s21
	s_addc_u32 s69, s74, 0
	global_load_lds_dwordx4 v[4:5], off
	v_add_u32_e32 v4, 0x6000, v142
	v_lshl_add_u64 v[2:3], v[2:3], 0, s[12:13]
	v_readfirstlane_b32 s21, v4
	v_add_u32_e32 v4, 0x8000, v142
	s_mov_b32 m0, s21
	v_readfirstlane_b32 s21, v4
	v_add_u32_e32 v9, 0xa000, v142
	global_load_lds_dwordx4 v[2:3], off
	v_lshl_add_u64 v[2:3], s[68:69], 0, v[0:1]
	s_mov_b32 m0, s21
	v_readfirstlane_b32 s21, v9
	v_add_u32_e32 v9, 0xc000, v142
	global_load_lds_dwordx4 v[2:3], off
	v_lshl_add_u64 v[4:5], v[2:3], 0, s[8:9]
	s_mov_b32 m0, s21
	v_readfirstlane_b32 s21, v9
	global_load_lds_dwordx4 v[4:5], off
	v_lshl_add_u64 v[4:5], v[2:3], 0, s[10:11]
	s_mov_b32 m0, s21
	v_lshl_add_u64 v[2:3], v[2:3], 0, s[12:13]
	global_load_lds_dwordx4 v[4:5], off
	v_add_u32_e32 v4, 0xe000, v142
	s_or_b32 s66, s70, s97
	v_readfirstlane_b32 s21, v4
	s_mov_b32 m0, s21
	v_ashrrev_i32_e32 v4, 6, v6
	global_load_lds_dwordx4 v[2:3], off
	v_lshrrev_b32_e32 v5, 30, v4
	s_ashr_i32 s67, s66, 31
	v_add_u32_e32 v5, v4, v5
	s_lshl_b64 s[68:69], s[66:67], 19
	v_bfe_u32 v2, v6, 4, 2
	v_bfe_u32 v3, v6, 1, 3
	v_and_b32_e32 v6, 0x7fffc, v5
	s_add_u32 s68, s34, s68
	v_sub_u32_e32 v4, v4, v6
	s_addc_u32 s69, s35, s69
	v_lshlrev_b32_e32 v144, 13, v4
	v_bitop3_b32 v4, v7, v3, 3 bitop3:0x6c
	v_bitop3_b32 v2, v2, v3, 4 bitop3:0x36
	v_lshl_add_u64 v[138:139], s[68:69], 0, v[0:1]
	s_add_u32 s68, s34, s20
	v_lshlrev_b32_e32 v5, 12, v5
	v_lshlrev_b32_e32 v4, 3, v4
	v_lshlrev_b32_e32 v2, 3, v2
	s_addc_u32 s69, s35, 0
	v_and_b32_e32 v143, 0xffffc000, v5
	v_lshl_add_u64 v[140:141], s[68:69], 0, v[0:1]
	s_mov_b64 s[68:69], 0
	v_lshlrev_b32_e32 v145, 1, v8
	v_lshlrev_b32_e32 v174, 1, v4
	v_lshlrev_b32_e32 v175, 1, v2
	s_mov_b32 vcc_lo, 0
	s_mov_b32 s86, 0
	v_mov_b32_e32 v4, 0
	v_mov_b32_e32 v5, v131
	v_mov_b32_e32 v6, v131
	v_mov_b32_e32 v7, v131
	v_mov_b32_e32 v12, 0
	v_mov_b32_e32 v13, v131
	v_mov_b32_e32 v14, v131
	v_mov_b32_e32 v15, v131
	v_mov_b32_e32 v0, 0
	v_mov_b32_e32 v1, v131
	v_mov_b32_e32 v2, v131
	v_mov_b32_e32 v3, v131
	v_mov_b32_e32 v8, 0
	v_mov_b32_e32 v9, v131
	v_mov_b32_e32 v10, v131
	v_mov_b32_e32 v11, v131
	v_mov_b32_e32 v16, 0
	v_mov_b32_e32 v17, v131
	v_mov_b32_e32 v18, v131
	v_mov_b32_e32 v19, v131
	v_mov_b32_e32 v20, 0
	v_mov_b32_e32 v21, v131
	v_mov_b32_e32 v22, v131
	v_mov_b32_e32 v23, v131
	v_mov_b32_e32 v24, 0
	v_mov_b32_e32 v25, v131
	v_mov_b32_e32 v26, v131
	v_mov_b32_e32 v27, v131
	v_mov_b32_e32 v28, 0
	v_mov_b32_e32 v29, v131
	v_mov_b32_e32 v30, v131
	v_mov_b32_e32 v31, v131
	v_mov_b32_e32 v32, 0
	v_mov_b32_e32 v33, v131
	v_mov_b32_e32 v34, v131
	v_mov_b32_e32 v35, v131
	v_mov_b32_e32 v36, 0
	v_mov_b32_e32 v37, v131
	v_mov_b32_e32 v38, v131
	v_mov_b32_e32 v39, v131
	v_mov_b32_e32 v40, 0
	v_mov_b32_e32 v41, v131
	v_mov_b32_e32 v42, v131
	v_mov_b32_e32 v43, v131
	v_mov_b32_e32 v44, 0
	v_mov_b32_e32 v45, v131
	v_mov_b32_e32 v46, v131
	v_mov_b32_e32 v47, v131
	v_mov_b32_e32 v48, 0
	v_mov_b32_e32 v49, v131
	v_mov_b32_e32 v50, v131
	v_mov_b32_e32 v51, v131
	v_mov_b32_e32 v52, 0
	v_mov_b32_e32 v53, v131
	v_mov_b32_e32 v54, v131
	v_mov_b32_e32 v55, v131
	v_mov_b32_e32 v56, 0
	v_mov_b32_e32 v57, v131
	v_mov_b32_e32 v58, v131
	v_mov_b32_e32 v59, v131
	v_mov_b32_e32 v60, 0
	v_mov_b32_e32 v61, v131
	v_mov_b32_e32 v62, v131
	v_mov_b32_e32 v63, v131
	v_mov_b32_e32 v64, 0
	v_mov_b32_e32 v65, v131
	v_mov_b32_e32 v66, v131
	v_mov_b32_e32 v67, v131
	v_mov_b32_e32 v68, 0
	v_mov_b32_e32 v69, v131
	v_mov_b32_e32 v70, v131
	v_mov_b32_e32 v71, v131
	v_mov_b32_e32 v72, 0
	v_mov_b32_e32 v73, v131
	v_mov_b32_e32 v74, v131
	v_mov_b32_e32 v75, v131
	v_mov_b32_e32 v76, 0
	v_mov_b32_e32 v77, v131
	v_mov_b32_e32 v78, v131
	v_mov_b32_e32 v79, v131
	v_mov_b32_e32 v80, 0
	v_mov_b32_e32 v81, v131
	v_mov_b32_e32 v82, v131
	v_mov_b32_e32 v83, v131
	v_mov_b32_e32 v84, 0
	v_mov_b32_e32 v85, v131
	v_mov_b32_e32 v86, v131
	v_mov_b32_e32 v87, v131
	v_mov_b32_e32 v88, 0
	v_mov_b32_e32 v89, v131
	v_mov_b32_e32 v90, v131
	v_mov_b32_e32 v91, v131
	v_mov_b32_e32 v92, 0
	v_mov_b32_e32 v93, v131
	v_mov_b32_e32 v94, v131
	v_mov_b32_e32 v95, v131
	v_mov_b32_e32 v96, 0
	v_mov_b32_e32 v97, v131
	v_mov_b32_e32 v98, v131
	v_mov_b32_e32 v99, v131
	v_mov_b32_e32 v100, 0
	v_mov_b32_e32 v101, v131
	v_mov_b32_e32 v102, v131
	v_mov_b32_e32 v103, v131
	v_mov_b32_e32 v104, 0
	v_mov_b32_e32 v105, v131
	v_mov_b32_e32 v106, v131
	v_mov_b32_e32 v107, v131
	v_mov_b32_e32 v108, 0
	v_mov_b32_e32 v109, v131
	v_mov_b32_e32 v110, v131
	v_mov_b32_e32 v111, v131
	v_mov_b32_e32 v112, 0
	v_mov_b32_e32 v113, v131
	v_mov_b32_e32 v114, v131
	v_mov_b32_e32 v115, v131
	v_mov_b32_e32 v116, 0
	v_mov_b32_e32 v117, v131
	v_mov_b32_e32 v118, v131
	v_mov_b32_e32 v119, v131
	v_mov_b32_e32 v120, 0
	v_mov_b32_e32 v121, v131
	v_mov_b32_e32 v122, v131
	v_mov_b32_e32 v123, v131
	v_mov_b32_e32 v124, 0
	v_mov_b32_e32 v125, v131
	v_mov_b32_e32 v126, v131
	v_mov_b32_e32 v127, v131
	s_waitcnt vmcnt(0) lgkmcnt(0)
	s_barrier
	v_add3_u32 v180, v143, v145, v174
	v_add3_u32 v245, v144, v145, v174
	v_add3_u32 v244, v143, v145, v175
	v_add3_u32 v246, v144, v145, v175
	v_readfirstlane_b32 s87, v142
	ds_read_b128 v[176:179], v180
	ds_read_b128 v[182:185], v180 offset:2048
	ds_read_b128 v[186:189], v180 offset:4096
	ds_read_b128 v[190:193], v180 offset:6144
	ds_read_b128 v[210:213], v245 offset:32768
	ds_read_b128 v[214:217], v245 offset:34816
	ds_read_b128 v[218:221], v245 offset:36864
	ds_read_b128 v[222:225], v245 offset:38912
	s_mov_b32 s86, 0
	s_mov_b64 s[68:69], 0
	s_add_u32 s87, s87, 0x10000
	s_add_u32 s70, s68, 0x4000080
	s_addc_u32 s71, s69, 0
	s_mov_b32 m0, s87
	v_lshl_add_u64 v[242:243], v[138:139], 0, s[70:71]
	global_load_lds_dwordx4 v[242:243], off
	s_add_u32 s70, s68, 0x4020080
	s_addc_u32 s71, s69, 0
	s_add_u32 m0, s87, 0x2000
	v_lshl_add_u64 v[242:243], v[138:139], 0, s[70:71]
	global_load_lds_dwordx4 v[242:243], off
	s_add_u32 s70, s68, 0x4040080
	s_addc_u32 s71, s69, 0
	s_add_u32 m0, s87, 0x4000
	v_lshl_add_u64 v[242:243], v[138:139], 0, s[70:71]
	global_load_lds_dwordx4 v[242:243], off
	s_add_u32 s70, s68, s14
	s_addc_u32 s71, s69, s15
	s_add_u32 m0, s87, 0x6000
	v_lshl_add_u64 v[242:243], v[138:139], 0, s[70:71]
	global_load_lds_dwordx4 v[242:243], off
	s_add_u32 s70, s68, s16
	s_addc_u32 s71, s69, s17
	s_add_u32 m0, s87, 0x8000
	v_lshl_add_u64 v[242:243], v[140:141], 0, s[70:71]
	global_load_lds_dwordx4 v[242:243], off
	s_add_u32 s70, s68, s18
	s_addc_u32 s71, s69, s19
	s_add_u32 m0, s87, 0xa000
	v_lshl_add_u64 v[242:243], v[140:141], 0, s[70:71]
	global_load_lds_dwordx4 v[242:243], off
	s_add_u32 s70, s68, s22
	s_addc_u32 s71, s69, s23
	s_add_u32 m0, s87, 0xc000
	v_lshl_add_u64 v[242:243], v[140:141], 0, s[70:71]
	global_load_lds_dwordx4 v[242:243], off
	s_add_u32 s70, s68, s36
	s_addc_u32 s71, s69, s37
	s_add_u32 m0, s87, 0xe000
	v_lshl_add_u64 v[242:243], v[140:141], 0, s[70:71]
	global_load_lds_dwordx4 v[242:243], off
	s_branch .Lg5_entry
.Lg5_top:
	s_waitcnt lgkmcnt(0)
	s_waitcnt vmcnt(0)
	s_barrier
	v_xor_b32_e32 v180, 0x10000, v180
	v_xor_b32_e32 v245, 0x10000, v245
	v_xor_b32_e32 v244, 0x10000, v244
	v_xor_b32_e32 v246, 0x10000, v246
	s_xor_b32 s87, s87, 0x10000
	ds_read_b128 v[176:179], v180
	ds_read_b128 v[182:185], v180 offset:2048
	ds_read_b128 v[186:189], v180 offset:4096
	ds_read_b128 v[190:193], v180 offset:6144
	ds_read_b128 v[210:213], v245 offset:32768
	ds_read_b128 v[214:217], v245 offset:34816
	ds_read_b128 v[218:221], v245 offset:36864
	ds_read_b128 v[222:225], v245 offset:38912
	v_mfma_f32_16x16x32_bf16 v[60:63], v[194:197], v[226:229], v[60:63]
	v_mfma_f32_16x16x32_bf16 v[56:59], v[194:197], v[230:233], v[56:59]
	s_add_u32 s70, s68, 0x4000080
	s_addc_u32 s71, s69, 0
	s_mov_b32 m0, s87
	v_lshl_add_u64 v[242:243], v[138:139], 0, s[70:71]
	global_load_lds_dwordx4 v[242:243], off
	v_mfma_f32_16x16x32_bf16 v[52:55], v[194:197], v[234:237], v[52:55]
	v_mfma_f32_16x16x32_bf16 v[48:51], v[194:197], v[238:241], v[48:51]
	s_add_u32 s70, s68, 0x4020080
	s_addc_u32 s71, s69, 0
	s_add_u32 m0, s87, 0x2000
	v_lshl_add_u64 v[242:243], v[138:139], 0, s[70:71]
	global_load_lds_dwordx4 v[242:243], off
	v_mfma_f32_16x16x32_bf16 v[44:47], v[198:201], v[226:229], v[44:47]
	v_mfma_f32_16x16x32_bf16 v[40:43], v[198:201], v[230:233], v[40:43]
	s_add_u32 s70, s68, 0x4040080
	s_addc_u32 s71, s69, 0
	s_add_u32 m0, s87, 0x4000
	v_lshl_add_u64 v[242:243], v[138:139], 0, s[70:71]
	global_load_lds_dwordx4 v[242:243], off
	v_mfma_f32_16x16x32_bf16 v[36:39], v[198:201], v[234:237], v[36:39]
	v_mfma_f32_16x16x32_bf16 v[32:35], v[198:201], v[238:241], v[32:35]
	s_add_u32 s70, s68, s14
	s_addc_u32 s71, s69, s15
	s_add_u32 m0, s87, 0x6000
	v_lshl_add_u64 v[242:243], v[138:139], 0, s[70:71]
	global_load_lds_dwordx4 v[242:243], off
	v_mfma_f32_16x16x32_bf16 v[28:31], v[202:205], v[226:229], v[28:31]
	v_mfma_f32_16x16x32_bf16 v[24:27], v[202:205], v[230:233], v[24:27]
	s_add_u32 s70, s68, s16
	s_addc_u32 s71, s69, s17
	s_add_u32 m0, s87, 0x8000
	v_lshl_add_u64 v[242:243], v[140:141], 0, s[70:71]
	global_load_lds_dwordx4 v[242:243], off
	v_mfma_f32_16x16x32_bf16 v[20:23], v[202:205], v[234:237], v[20:23]
	v_mfma_f32_16x16x32_bf16 v[16:19], v[202:205], v[238:241], v[16:19]
	s_add_u32 s70, s68, s18
	s_addc_u32 s71, s69, s19
	s_add_u32 m0, s87, 0xa000
	v_lshl_add_u64 v[242:243], v[140:141], 0, s[70:71]
	global_load_lds_dwordx4 v[242:243], off
	v_mfma_f32_16x16x32_bf16 v[8:11], v[206:209], v[226:229], v[8:11]
	v_mfma_f32_16x16x32_bf16 v[0:3], v[206:209], v[230:233], v[0:3]
	s_add_u32 s70, s68, s22
	s_addc_u32 s71, s69, s23
	s_add_u32 m0, s87, 0xc000
	v_lshl_add_u64 v[242:243], v[140:141], 0, s[70:71]
	global_load_lds_dwordx4 v[242:243], off
	v_mfma_f32_16x16x32_bf16 v[12:15], v[206:209], v[234:237], v[12:15]
	v_mfma_f32_16x16x32_bf16 v[4:7], v[206:209], v[238:241], v[4:7]
	s_add_u32 s70, s68, s36
	s_addc_u32 s71, s69, s37
	s_add_u32 m0, s87, 0xe000
	v_lshl_add_u64 v[242:243], v[140:141], 0, s[70:71]
	global_load_lds_dwordx4 v[242:243], off
.Lg5_entry:
	ds_read_b128 v[194:197], v180 offset:8192
	ds_read_b128 v[198:201], v180 offset:10240
	ds_read_b128 v[202:205], v180 offset:12288
	ds_read_b128 v[206:209], v180 offset:14336
	s_waitcnt lgkmcnt(4)
	v_mfma_f32_16x16x32_bf16 v[124:127], v[176:179], v[210:213], v[124:127]
	v_mfma_f32_16x16x32_bf16 v[120:123], v[176:179], v[214:217], v[120:123]
	v_mfma_f32_16x16x32_bf16 v[116:119], v[176:179], v[218:221], v[116:119]
	v_mfma_f32_16x16x32_bf16 v[112:115], v[176:179], v[222:225], v[112:115]
	v_mfma_f32_16x16x32_bf16 v[108:111], v[182:185], v[210:213], v[108:111]
	v_mfma_f32_16x16x32_bf16 v[104:107], v[182:185], v[214:217], v[104:107]
	v_mfma_f32_16x16x32_bf16 v[100:103], v[182:185], v[218:221], v[100:103]
	v_mfma_f32_16x16x32_bf16 v[96:99], v[182:185], v[222:225], v[96:99]
	v_mfma_f32_16x16x32_bf16 v[92:95], v[186:189], v[210:213], v[92:95]
	v_mfma_f32_16x16x32_bf16 v[88:91], v[186:189], v[214:217], v[88:91]
	v_mfma_f32_16x16x32_bf16 v[84:87], v[186:189], v[218:221], v[84:87]
	v_mfma_f32_16x16x32_bf16 v[80:83], v[186:189], v[222:225], v[80:83]
	v_mfma_f32_16x16x32_bf16 v[76:79], v[190:193], v[210:213], v[76:79]
	v_mfma_f32_16x16x32_bf16 v[72:75], v[190:193], v[214:217], v[72:75]
	v_mfma_f32_16x16x32_bf16 v[68:71], v[190:193], v[218:221], v[68:71]
	v_mfma_f32_16x16x32_bf16 v[64:67], v[190:193], v[222:225], v[64:67]
	ds_read_b128 v[176:179], v244
	ds_read_b128 v[182:185], v244 offset:2048
	ds_read_b128 v[186:189], v244 offset:4096
	ds_read_b128 v[190:193], v244 offset:6144
	ds_read_b128 v[226:229], v246 offset:32768
	ds_read_b128 v[230:233], v246 offset:34816
	ds_read_b128 v[234:237], v246 offset:36864
	ds_read_b128 v[238:241], v246 offset:38912
	s_waitcnt lgkmcnt(8)
	v_mfma_f32_16x16x32_bf16 v[60:63], v[194:197], v[210:213], v[60:63]
	v_mfma_f32_16x16x32_bf16 v[56:59], v[194:197], v[214:217], v[56:59]
	v_mfma_f32_16x16x32_bf16 v[52:55], v[194:197], v[218:221], v[52:55]
	v_mfma_f32_16x16x32_bf16 v[48:51], v[194:197], v[222:225], v[48:51]
	v_mfma_f32_16x16x32_bf16 v[44:47], v[198:201], v[210:213], v[44:47]
	v_mfma_f32_16x16x32_bf16 v[40:43], v[198:201], v[214:217], v[40:43]
	v_mfma_f32_16x16x32_bf16 v[36:39], v[198:201], v[218:221], v[36:39]
	v_mfma_f32_16x16x32_bf16 v[32:35], v[198:201], v[222:225], v[32:35]
	v_mfma_f32_16x16x32_bf16 v[28:31], v[202:205], v[210:213], v[28:31]
	v_mfma_f32_16x16x32_bf16 v[24:27], v[202:205], v[214:217], v[24:27]
	v_mfma_f32_16x16x32_bf16 v[20:23], v[202:205], v[218:221], v[20:23]
	v_mfma_f32_16x16x32_bf16 v[16:19], v[202:205], v[222:225], v[16:19]
	v_mfma_f32_16x16x32_bf16 v[8:11], v[206:209], v[210:213], v[8:11]
	v_mfma_f32_16x16x32_bf16 v[0:3], v[206:209], v[214:217], v[0:3]
	v_mfma_f32_16x16x32_bf16 v[12:15], v[206:209], v[218:221], v[12:15]
	v_mfma_f32_16x16x32_bf16 v[4:7], v[206:209], v[222:225], v[4:7]
	ds_read_b128 v[194:197], v244 offset:8192
	ds_read_b128 v[198:201], v244 offset:10240
	ds_read_b128 v[202:205], v244 offset:12288
	ds_read_b128 v[206:209], v244 offset:14336
	s_waitcnt lgkmcnt(4)
	v_mfma_f32_16x16x32_bf16 v[124:127], v[176:179], v[226:229], v[124:127]
	v_mfma_f32_16x16x32_bf16 v[120:123], v[176:179], v[230:233], v[120:123]
	v_mfma_f32_16x16x32_bf16 v[116:119], v[176:179], v[234:237], v[116:119]
	v_mfma_f32_16x16x32_bf16 v[112:115], v[176:179], v[238:241], v[112:115]
	v_mfma_f32_16x16x32_bf16 v[108:111], v[182:185], v[226:229], v[108:111]
	v_mfma_f32_16x16x32_bf16 v[104:107], v[182:185], v[230:233], v[104:107]
	v_mfma_f32_16x16x32_bf16 v[100:103], v[182:185], v[234:237], v[100:103]
	v_mfma_f32_16x16x32_bf16 v[96:99], v[182:185], v[238:241], v[96:99]
	v_mfma_f32_16x16x32_bf16 v[92:95], v[186:189], v[226:229], v[92:95]
	v_mfma_f32_16x16x32_bf16 v[88:91], v[186:189], v[230:233], v[88:91]
	v_mfma_f32_16x16x32_bf16 v[84:87], v[186:189], v[234:237], v[84:87]
	v_mfma_f32_16x16x32_bf16 v[80:83], v[186:189], v[238:241], v[80:83]
	v_mfma_f32_16x16x32_bf16 v[76:79], v[190:193], v[226:229], v[76:79]
	v_mfma_f32_16x16x32_bf16 v[72:75], v[190:193], v[230:233], v[72:75]
	v_mfma_f32_16x16x32_bf16 v[68:71], v[190:193], v[234:237], v[68:71]
	v_mfma_f32_16x16x32_bf16 v[64:67], v[190:193], v[238:241], v[64:67]
	s_add_u32 s68, s68, 0x80
	s_addc_u32 s69, s69, 0
	s_add_i32 s86, s86, 1
	s_cmp_lt_u32 s86, 15
	s_cbranch_scc1 .Lg5_top
	s_waitcnt lgkmcnt(0)
	s_waitcnt vmcnt(0)
	s_barrier
	v_xor_b32_e32 v180, 0x10000, v180
	v_xor_b32_e32 v245, 0x10000, v245
	v_xor_b32_e32 v244, 0x10000, v244
	v_xor_b32_e32 v246, 0x10000, v246
	s_xor_b32 s87, s87, 0x10000
	ds_read_b128 v[176:179], v180
	ds_read_b128 v[182:185], v180 offset:2048
	ds_read_b128 v[186:189], v180 offset:4096
	ds_read_b128 v[190:193], v180 offset:6144
	ds_read_b128 v[210:213], v245 offset:32768
	ds_read_b128 v[214:217], v245 offset:34816
	ds_read_b128 v[218:221], v245 offset:36864
	ds_read_b128 v[222:225], v245 offset:38912
	v_mfma_f32_16x16x32_bf16 v[60:63], v[194:197], v[226:229], v[60:63]
	v_mfma_f32_16x16x32_bf16 v[56:59], v[194:197], v[230:233], v[56:59]
	v_mfma_f32_16x16x32_bf16 v[52:55], v[194:197], v[234:237], v[52:55]
	v_mfma_f32_16x16x32_bf16 v[48:51], v[194:197], v[238:241], v[48:51]
	v_mfma_f32_16x16x32_bf16 v[44:47], v[198:201], v[226:229], v[44:47]
	v_mfma_f32_16x16x32_bf16 v[40:43], v[198:201], v[230:233], v[40:43]
	v_mfma_f32_16x16x32_bf16 v[36:39], v[198:201], v[234:237], v[36:39]
	v_mfma_f32_16x16x32_bf16 v[32:35], v[198:201], v[238:241], v[32:35]
	v_mfma_f32_16x16x32_bf16 v[28:31], v[202:205], v[226:229], v[28:31]
	v_mfma_f32_16x16x32_bf16 v[24:27], v[202:205], v[230:233], v[24:27]
	v_mfma_f32_16x16x32_bf16 v[20:23], v[202:205], v[234:237], v[20:23]
	v_mfma_f32_16x16x32_bf16 v[16:19], v[202:205], v[238:241], v[16:19]
	v_mfma_f32_16x16x32_bf16 v[8:11], v[206:209], v[226:229], v[8:11]
	v_mfma_f32_16x16x32_bf16 v[0:3], v[206:209], v[230:233], v[0:3]
	v_mfma_f32_16x16x32_bf16 v[12:15], v[206:209], v[234:237], v[12:15]
	v_mfma_f32_16x16x32_bf16 v[4:7], v[206:209], v[238:241], v[4:7]
	ds_read_b128 v[194:197], v180 offset:8192
	ds_read_b128 v[198:201], v180 offset:10240
	ds_read_b128 v[202:205], v180 offset:12288
	ds_read_b128 v[206:209], v180 offset:14336
	s_waitcnt lgkmcnt(4)
	v_mfma_f32_16x16x32_bf16 v[124:127], v[176:179], v[210:213], v[124:127]
	v_mfma_f32_16x16x32_bf16 v[120:123], v[176:179], v[214:217], v[120:123]
	v_mfma_f32_16x16x32_bf16 v[116:119], v[176:179], v[218:221], v[116:119]
	v_mfma_f32_16x16x32_bf16 v[112:115], v[176:179], v[222:225], v[112:115]
	v_mfma_f32_16x16x32_bf16 v[108:111], v[182:185], v[210:213], v[108:111]
	v_mfma_f32_16x16x32_bf16 v[104:107], v[182:185], v[214:217], v[104:107]
	v_mfma_f32_16x16x32_bf16 v[100:103], v[182:185], v[218:221], v[100:103]
	v_mfma_f32_16x16x32_bf16 v[96:99], v[182:185], v[222:225], v[96:99]
	v_mfma_f32_16x16x32_bf16 v[92:95], v[186:189], v[210:213], v[92:95]
	v_mfma_f32_16x16x32_bf16 v[88:91], v[186:189], v[214:217], v[88:91]
	v_mfma_f32_16x16x32_bf16 v[84:87], v[186:189], v[218:221], v[84:87]
	v_mfma_f32_16x16x32_bf16 v[80:83], v[186:189], v[222:225], v[80:83]
	v_mfma_f32_16x16x32_bf16 v[76:79], v[190:193], v[210:213], v[76:79]
	v_mfma_f32_16x16x32_bf16 v[72:75], v[190:193], v[214:217], v[72:75]
	v_mfma_f32_16x16x32_bf16 v[68:71], v[190:193], v[218:221], v[68:71]
	v_mfma_f32_16x16x32_bf16 v[64:67], v[190:193], v[222:225], v[64:67]
	ds_read_b128 v[176:179], v244
	ds_read_b128 v[182:185], v244 offset:2048
	ds_read_b128 v[186:189], v244 offset:4096
	ds_read_b128 v[190:193], v244 offset:6144
	ds_read_b128 v[226:229], v246 offset:32768
	ds_read_b128 v[230:233], v246 offset:34816
	ds_read_b128 v[234:237], v246 offset:36864
	ds_read_b128 v[238:241], v246 offset:38912
	s_waitcnt lgkmcnt(8)
	v_mfma_f32_16x16x32_bf16 v[60:63], v[194:197], v[210:213], v[60:63]
	v_mfma_f32_16x16x32_bf16 v[56:59], v[194:197], v[214:217], v[56:59]
	v_mfma_f32_16x16x32_bf16 v[52:55], v[194:197], v[218:221], v[52:55]
	v_mfma_f32_16x16x32_bf16 v[48:51], v[194:197], v[222:225], v[48:51]
	v_mfma_f32_16x16x32_bf16 v[44:47], v[198:201], v[210:213], v[44:47]
	v_mfma_f32_16x16x32_bf16 v[40:43], v[198:201], v[214:217], v[40:43]
	v_mfma_f32_16x16x32_bf16 v[36:39], v[198:201], v[218:221], v[36:39]
	v_mfma_f32_16x16x32_bf16 v[32:35], v[198:201], v[222:225], v[32:35]
	v_mfma_f32_16x16x32_bf16 v[28:31], v[202:205], v[210:213], v[28:31]
	v_mfma_f32_16x16x32_bf16 v[24:27], v[202:205], v[214:217], v[24:27]
	v_mfma_f32_16x16x32_bf16 v[20:23], v[202:205], v[218:221], v[20:23]
	v_mfma_f32_16x16x32_bf16 v[16:19], v[202:205], v[222:225], v[16:19]
	v_mfma_f32_16x16x32_bf16 v[8:11], v[206:209], v[210:213], v[8:11]
	v_mfma_f32_16x16x32_bf16 v[0:3], v[206:209], v[214:217], v[0:3]
	v_mfma_f32_16x16x32_bf16 v[12:15], v[206:209], v[218:221], v[12:15]
	v_mfma_f32_16x16x32_bf16 v[4:7], v[206:209], v[222:225], v[4:7]
	ds_read_b128 v[194:197], v244 offset:8192
	ds_read_b128 v[198:201], v244 offset:10240
	ds_read_b128 v[202:205], v244 offset:12288
	ds_read_b128 v[206:209], v244 offset:14336
	s_waitcnt lgkmcnt(4)
	v_mfma_f32_16x16x32_bf16 v[124:127], v[176:179], v[226:229], v[124:127]
	v_mfma_f32_16x16x32_bf16 v[120:123], v[176:179], v[230:233], v[120:123]
	v_mfma_f32_16x16x32_bf16 v[116:119], v[176:179], v[234:237], v[116:119]
	v_mfma_f32_16x16x32_bf16 v[112:115], v[176:179], v[238:241], v[112:115]
	v_mfma_f32_16x16x32_bf16 v[108:111], v[182:185], v[226:229], v[108:111]
	v_mfma_f32_16x16x32_bf16 v[104:107], v[182:185], v[230:233], v[104:107]
	v_mfma_f32_16x16x32_bf16 v[100:103], v[182:185], v[234:237], v[100:103]
	v_mfma_f32_16x16x32_bf16 v[96:99], v[182:185], v[238:241], v[96:99]
	v_mfma_f32_16x16x32_bf16 v[92:95], v[186:189], v[226:229], v[92:95]
	v_mfma_f32_16x16x32_bf16 v[88:91], v[186:189], v[230:233], v[88:91]
	v_mfma_f32_16x16x32_bf16 v[84:87], v[186:189], v[234:237], v[84:87]
	v_mfma_f32_16x16x32_bf16 v[80:83], v[186:189], v[238:241], v[80:83]
	v_mfma_f32_16x16x32_bf16 v[76:79], v[190:193], v[226:229], v[76:79]
	v_mfma_f32_16x16x32_bf16 v[72:75], v[190:193], v[230:233], v[72:75]
	v_mfma_f32_16x16x32_bf16 v[68:71], v[190:193], v[234:237], v[68:71]
	v_mfma_f32_16x16x32_bf16 v[64:67], v[190:193], v[238:241], v[64:67]
	s_add_u32 s68, s68, 0x80
	s_addc_u32 s69, s69, 0
	s_add_i32 s86, s86, 1
	s_waitcnt lgkmcnt(0)
	s_waitcnt vmcnt(0)
	s_barrier
	v_mfma_f32_16x16x32_bf16 v[60:63], v[194:197], v[226:229], v[60:63]
	v_mfma_f32_16x16x32_bf16 v[56:59], v[194:197], v[230:233], v[56:59]
	v_mfma_f32_16x16x32_bf16 v[52:55], v[194:197], v[234:237], v[52:55]
	v_mfma_f32_16x16x32_bf16 v[48:51], v[194:197], v[238:241], v[48:51]
	v_mfma_f32_16x16x32_bf16 v[44:47], v[198:201], v[226:229], v[44:47]
	v_mfma_f32_16x16x32_bf16 v[40:43], v[198:201], v[230:233], v[40:43]
	v_mfma_f32_16x16x32_bf16 v[36:39], v[198:201], v[234:237], v[36:39]
	v_mfma_f32_16x16x32_bf16 v[32:35], v[198:201], v[238:241], v[32:35]
	v_mfma_f32_16x16x32_bf16 v[28:31], v[202:205], v[226:229], v[28:31]
	v_mfma_f32_16x16x32_bf16 v[24:27], v[202:205], v[230:233], v[24:27]
	v_mfma_f32_16x16x32_bf16 v[20:23], v[202:205], v[234:237], v[20:23]
	v_mfma_f32_16x16x32_bf16 v[16:19], v[202:205], v[238:241], v[16:19]
	v_mfma_f32_16x16x32_bf16 v[8:11], v[206:209], v[226:229], v[8:11]
	v_mfma_f32_16x16x32_bf16 v[0:3], v[206:209], v[230:233], v[0:3]
	v_mfma_f32_16x16x32_bf16 v[12:15], v[206:209], v[234:237], v[12:15]
	v_mfma_f32_16x16x32_bf16 v[4:7], v[206:209], v[238:241], v[4:7]
	s_nop 7
	s_nop 7
	s_mov_b32 s87, 0x80000
	s_mov_b32 s87, 0x80000
	s_mov_b64 s[70:71], 0
	s_mov_b64 vcc, exec
	s_branch .LBB0_666

.LBB0_810:
	s_ashr_i32 s4, s17, 31
	s_lshr_b32 s4, s4, 29
	s_add_i32 s4, s17, s4
	s_ashr_i32 s12, s4, 3
	s_lshl_b32 s18, s12, 6
	s_add_i32 s4, s18, 0xfffff580
	v_or_b32_e32 v0, s18, v14
	s_cmp_gt_u32 s4, 0xfffff7ff
	v_subrev_u32_e32 v1, 64, v0
	s_cselect_b64 vcc, -1, 0
	v_cndmask_b32_e32 v1, -1, v1, vcc
	v_cmp_gt_i32_e32 vcc, s16, v0
	s_mul_i32 s8, s12, 0xffd70000
	v_add_u32_e32 v6, s8, v22
	v_cndmask_b32_e32 v10, v1, v0, vcc
	v_cmp_lt_i32_e64 s[4:5], -1, v10
	v_lshl_add_u64 v[4:5], v[10:11], 2, s[58:59]
	v_mov_b32_e32 v10, v11
	v_mov_b64_e32 v[0:1], v[10:11]
	v_mov_b64_e32 v[2:3], v[10:11]
	s_waitcnt lgkmcnt(0)
	s_barrier
	s_and_saveexec_b64 s[8:9], s[4:5]
	s_cbranch_execz .LBB0_812
	v_ashrrev_i32_e32 v7, 31, v6
	v_lshl_add_u64 v[0:1], v[6:7], 2, v[4:5]
	global_load_dwordx4 v[0:3], v[0:1], off
	v_add_u32_e32 v56, 0x14800, v6
	v_ashrrev_i32_e32 v57, 31, v56
	v_lshl_add_u64 v[56:57], v[56:57], 2, v[4:5]
	global_load_dwordx4 v[40:43], v[56:57], off
	v_add_u32_e32 v56, 0x29000, v6
	v_ashrrev_i32_e32 v57, 31, v56
	v_lshl_add_u64 v[56:57], v[56:57], 2, v[4:5]
	global_load_dwordx4 v[44:47], v[56:57], off
	v_add_u32_e32 v56, 0x3d800, v6
	v_ashrrev_i32_e32 v57, 31, v56
	v_lshl_add_u64 v[56:57], v[56:57], 2, v[4:5]
	global_load_dwordx4 v[48:51], v[56:57], off
.LBB0_812:
	s_or_b64 exec, exec, s[8:9]
	s_lshl_b32 s8, s12, 10
	s_and_b64 vcc, exec, s[0:1]
	s_sub_i32 s12, 0, s8
	s_cbranch_vccnz .LBB0_814
	s_add_i32 s8, s12, s3
	v_add_u32_e32 v24, s8, v8
	v_ashrrev_i32_e32 v25, 31, v24
	v_lshl_add_u64 v[24:25], v[24:25], 2, s[56:57]
	global_load_dword v10, v[24:25], off
	global_load_dword v52, v[24:25], off offset:128
	global_load_dword v53, v[24:25], off offset:256
	global_load_dword v54, v[24:25], off offset:384
	s_waitcnt vmcnt(0)
	v_pk_mul_f32 v[0:1], v[0:1], v[10:11] op_sel_hi:[1,0]
	v_pk_mul_f32 v[2:3], v[2:3], v[10:11] op_sel_hi:[1,0]
.LBB0_814:
	v_mov_b32_e32 v10, v11
	s_waitcnt vmcnt(0)
	ds_write_b128 v16, v[0:3]
	v_mov_b64_e32 v[0:1], v[10:11]
	v_mov_b64_e32 v[2:3], v[10:11]
	s_and_saveexec_b64 s[8:9], s[4:5]
	s_cbranch_execz .LBB0_816
	v_mov_b64_e32 v[0:1], v[40:41]
	v_mov_b64_e32 v[2:3], v[42:43]
.LBB0_816:
	s_or_b64 exec, exec, s[8:9]
	s_and_b64 vcc, exec, s[0:1]
	s_add_i32 s8, s3, s12
	s_cbranch_vccnz .LBB0_818
	s_ashr_i32 s9, s8, 31
	v_lshl_add_u64 v[24:25], s[8:9], 0, v[8:9]
	v_lshl_add_u64 v[24:25], v[24:25], 2, s[56:57]
	v_mov_b32_e32 v10, v52
	s_waitcnt vmcnt(0)
	v_pk_mul_f32 v[0:1], v[0:1], v[10:11] op_sel_hi:[1,0]
	v_pk_mul_f32 v[2:3], v[2:3], v[10:11] op_sel_hi:[1,0]
.LBB0_818:
	v_mov_b32_e32 v10, v11
	s_waitcnt vmcnt(0)
	ds_write_b128 v18, v[0:3]
	v_mov_b64_e32 v[0:1], v[10:11]
	v_mov_b64_e32 v[2:3], v[10:11]
	s_and_saveexec_b64 s[12:13], s[4:5]
	s_cbranch_execz .LBB0_820
	v_mov_b64_e32 v[0:1], v[44:45]
	v_mov_b64_e32 v[2:3], v[46:47]
.LBB0_820:
	s_or_b64 exec, exec, s[12:13]
	s_and_b64 vcc, exec, s[0:1]
	s_cbranch_vccnz .LBB0_822
	s_ashr_i32 s9, s8, 31
	v_lshl_add_u64 v[24:25], s[8:9], 0, v[8:9]
	v_lshl_add_u64 v[24:25], v[24:25], 2, s[56:57]
	v_mov_b32_e32 v10, v53
	s_waitcnt vmcnt(0)
	v_pk_mul_f32 v[0:1], v[0:1], v[10:11] op_sel_hi:[1,0]
	v_pk_mul_f32 v[2:3], v[2:3], v[10:11] op_sel_hi:[1,0]
.LBB0_822:
	v_mov_b32_e32 v10, v11
	s_waitcnt vmcnt(0)
	ds_write_b128 v19, v[0:3]
	v_mov_b64_e32 v[0:1], v[10:11]
	v_mov_b64_e32 v[2:3], v[10:11]
	s_and_saveexec_b64 s[12:13], s[4:5]
	s_cbranch_execz .LBB0_824
	v_mov_b64_e32 v[0:1], v[48:49]
	v_mov_b64_e32 v[2:3], v[50:51]
.LBB0_824:
	s_or_b64 exec, exec, s[12:13]
	s_and_b64 vcc, exec, s[6:7]
	s_cbranch_vccz .LBB0_826
	s_ashr_i32 s9, s8, 31
	v_lshl_add_u64 v[4:5], s[8:9], 0, v[8:9]
	v_lshl_add_u64 v[4:5], v[4:5], 2, s[56:57]
	v_mov_b32_e32 v6, v54
	s_waitcnt vmcnt(0)
	v_pk_mul_f32 v[4:5], v[0:1], v[6:7] op_sel_hi:[1,0]
	v_pk_mul_f32 v[6:7], v[2:3], v[6:7] op_sel_hi:[1,0]
	s_cbranch_execnz .LBB0_809
	s_branch .LBB0_827

.LBB0_1028:
	v_lshl_add_u32 v230, s70, 2, v129
	v_mul_hi_i32 v136, v230, s64
	v_lshrrev_b32_e32 v137, 31, v136
	ds_read_b32 v138, v149
	v_add_u32_e32 v136, v136, v137
	v_lshl_add_u32 v136, v136, 1, v136
	v_sub_u32_e32 v136, v230, v136
	v_cmp_eq_u32_e32 vcc, 2, v136
	v_lshl_add_u32 v231, s69, 8, v148
	v_mov_b32_e32 v136, v120
	v_mov_b32_e32 v137, v124
	s_waitcnt lgkmcnt(0)
	v_pk_mul_f32 v[142:143], v[136:137], v[138:139] op_sel_hi:[1,0]
	v_or_b32_e32 v136, v231, v133
	v_ashrrev_i32_e32 v137, 31, v136
	s_cbranch_vccz .Lq_pf_skip0
	v_or_b32_e32 v251, v231, v133
	v_lshlrev_b32_e32 v251, 7, v251
	v_lshl_add_u32 v251, v130, 2, v251
	s_mov_b64 s[56:57], s[6:7]
	s_mov_b64 s[72:73], s[8:9]
	global_load_dword v236, v251, s[56:57]
	global_load_dword v237, v251, s[72:73]
	global_load_dword v238, v251, s[56:57] offset:128
	global_load_dword v239, v251, s[72:73] offset:128
	global_load_dword v240, v251, s[56:57] offset:256
	global_load_dword v241, v251, s[72:73] offset:256
	global_load_dword v242, v251, s[56:57] offset:384
	global_load_dword v243, v251, s[72:73] offset:384
	global_load_dword v244, v251, s[56:57] offset:64
	global_load_dword v245, v251, s[72:73] offset:64
	global_load_dword v246, v251, s[56:57] offset:192
	global_load_dword v247, v251, s[72:73] offset:192
	global_load_dword v248, v251, s[56:57] offset:320
	global_load_dword v249, v251, s[72:73] offset:320
.Lq_pf_skip0:
	s_and_saveexec_b64 s[48:49], vcc
	s_cbranch_execz .LBB0_1030
	v_lshlrev_b64 v[140:141], 7, v[136:137]
	v_lshl_or_b32 v140, v130, 2, v140
	v_lshl_add_u64 v[144:145], s[6:7], 0, v[140:141]
	v_lshl_add_u64 v[140:141], s[8:9], 0, v[140:141]
	s_waitcnt vmcnt(12)
	v_mov_b32_e32 v120, v236
	v_mov_b32_e32 v124, v237
	v_pk_mul_f32 v[140:141], v[142:143], v[120:121] op_sel_hi:[1,0]
	v_pk_mul_f32 v[144:145], v[142:143], v[124:125] op_sel:[1,0] op_sel_hi:[0,0]
	v_pk_fma_f32 v[142:143], v[142:143], v[120:121], v[144:145] op_sel_hi:[1,0,1] neg_lo:[0,0,1] neg_hi:[0,0,1]
	s_nop 0
	v_add_f32_e32 v142, v140, v144
.LBB0_1030:
	s_or_b64 exec, exec, s[48:49]
	s_cbranch_vccz .Lq_pf_skip1
	global_load_dword v236, v251, s[56:57] offset:448
	global_load_dword v237, v251, s[72:73] offset:448
.Lq_pf_skip1:
	ds_read_b32 v140, v149 offset:4
	v_cvt_pk_bf16_f32 v120, v143, s0
	ds_write_b16 v150, v120
	v_cvt_pk_bf16_f32 v120, v142, s0
	ds_write_b16 v151, v120 offset:64
	v_or_b32_e32 v120, 1, v133
	v_mov_b32_e32 v124, v121
	v_or_b32_e32 v120, v231, v120
	s_waitcnt lgkmcnt(2)
	v_pk_mul_f32 v[124:125], v[124:125], v[140:141] op_sel_hi:[1,0]
	v_ashrrev_i32_e32 v121, 31, v120
	s_and_saveexec_b64 s[48:49], vcc
	s_cbranch_execz .LBB0_1032
	v_lshlrev_b64 v[142:143], 7, v[120:121]
	v_lshl_or_b32 v142, v130, 2, v142
	v_lshl_add_u64 v[144:145], s[6:7], 0, v[142:143]
	v_lshl_add_u64 v[142:143], s[8:9], 0, v[142:143]
	s_waitcnt vmcnt(12)
	v_mov_b32_e32 v144, v238
	s_nop 0
	v_mov_b32_e32 v142, v239
	v_pk_mul_f32 v[146:147], v[124:125], v[144:145] op_sel_hi:[1,0]
	v_pk_mul_f32 v[142:143], v[124:125], v[142:143] op_sel:[1,0] op_sel_hi:[0,0]
	v_pk_fma_f32 v[124:125], v[124:125], v[144:145], v[142:143] op_sel_hi:[1,0,1] neg_lo:[0,0,1] neg_hi:[0,0,1]
	s_nop 0
	v_add_f32_e32 v124, v146, v142
.LBB0_1032:
	s_or_b64 exec, exec, s[48:49]
	s_cbranch_vccz .Lq_pf_skip2
	s_add_u32 s56, s56, 0x800
	s_addc_u32 s57, s57, 0
	s_add_u32 s72, s72, 0x800
	s_addc_u32 s73, s73, 0
	global_load_dword v238, v251, s[56:57]
	global_load_dword v239, v251, s[72:73]
.Lq_pf_skip2:
	ds_read_b32 v142, v149 offset:8
	v_cvt_pk_bf16_f32 v125, v125, s0
	v_cvt_pk_bf16_f32 v124, v124, s0
	ds_write_b16 v151, v125 offset:144
	ds_write_b16 v152, v124 offset:64
	v_mov_b32_e32 v124, v122
	v_mov_b32_e32 v125, v126
	v_or_b32_e32 v122, 2, v133
	s_waitcnt lgkmcnt(2)
	v_pk_mul_f32 v[146:147], v[124:125], v[142:143] op_sel_hi:[1,0]
	v_or_b32_e32 v124, v231, v122
	v_ashrrev_i32_e32 v125, 31, v124
	s_and_saveexec_b64 s[48:49], vcc
	s_cbranch_execz .LBB0_1034
	v_lshlrev_b64 v[144:145], 7, v[124:125]
	v_lshl_or_b32 v144, v130, 2, v144
	v_lshl_add_u64 v[232:233], s[6:7], 0, v[144:145]
	v_lshl_add_u64 v[144:145], s[8:9], 0, v[144:145]
	s_waitcnt vmcnt(12)
	v_mov_b32_e32 v122, v240
	v_mov_b32_e32 v126, v241
	v_pk_mul_f32 v[144:145], v[146:147], v[122:123] op_sel_hi:[1,0]
	v_pk_mul_f32 v[232:233], v[146:147], v[126:127] op_sel:[1,0] op_sel_hi:[0,0]
	v_pk_fma_f32 v[146:147], v[146:147], v[122:123], v[232:233] op_sel_hi:[1,0,1] neg_lo:[0,0,1] neg_hi:[0,0,1]
	s_nop 0
	v_add_f32_e32 v146, v144, v232
.LBB0_1034:
	s_or_b64 exec, exec, s[48:49]
	s_cbranch_vccz .Lq_pf_skip3
	global_load_dword v240, v251, s[56:57] offset:128
	global_load_dword v241, v251, s[72:73] offset:128
.Lq_pf_skip3:
	ds_read_b32 v144, v149 offset:12
	v_cvt_pk_bf16_f32 v122, v147, s0
	ds_write_b16 v153, v122
	v_cvt_pk_bf16_f32 v122, v146, s0
	ds_write_b16 v154, v122 offset:64
	v_or_b32_e32 v122, 3, v133
	v_mov_b32_e32 v126, v123
	v_or_b32_e32 v122, v231, v122
	s_waitcnt lgkmcnt(2)
	v_pk_mul_f32 v[126:127], v[126:127], v[144:145] op_sel_hi:[1,0]
	v_ashrrev_i32_e32 v123, 31, v122
	s_and_saveexec_b64 s[48:49], vcc
	s_cbranch_execz .LBB0_1036
	v_lshlrev_b64 v[146:147], 7, v[122:123]
	v_lshl_or_b32 v146, v130, 2, v146
	v_lshl_add_u64 v[232:233], s[6:7], 0, v[146:147]
	v_lshl_add_u64 v[146:147], s[8:9], 0, v[146:147]
	s_waitcnt vmcnt(12)
	v_mov_b32_e32 v232, v242
	s_nop 0
	v_mov_b32_e32 v146, v243
	v_pk_mul_f32 v[234:235], v[126:127], v[232:233] op_sel_hi:[1,0]
	v_pk_mul_f32 v[146:147], v[126:127], v[146:147] op_sel:[1,0] op_sel_hi:[0,0]
	v_pk_fma_f32 v[126:127], v[126:127], v[232:233], v[146:147] op_sel_hi:[1,0,1] neg_lo:[0,0,1] neg_hi:[0,0,1]
	s_nop 0
	v_add_f32_e32 v126, v234, v146
.LBB0_1036:
	s_or_b64 exec, exec, s[48:49]
	s_cbranch_vccz .Lq_pf_skip4
	global_load_dword v242, v251, s[56:57] offset:256
	global_load_dword v243, v251, s[72:73] offset:256
.Lq_pf_skip4:
	v_cvt_pk_bf16_f32 v127, v127, s0
	v_cvt_pk_bf16_f32 v126, v126, s0
	v_mov_b32_e32 v139, v138
	ds_write_b16 v155, v127
	ds_write_b16 v156, v126 offset:64
	v_mov_b32_e32 v126, v112
	v_mov_b32_e32 v127, v116
	v_pk_mul_f32 v[126:127], v[126:127], v[138:139]
	s_and_saveexec_b64 s[48:49], vcc
	s_cbranch_execz .LBB0_1038
	v_lshlrev_b64 v[136:137], 7, v[136:137]
	v_lshl_or_b32 v136, v132, 2, v136
	v_lshl_add_u64 v[138:139], s[6:7], 0, v[136:137]
	v_lshl_add_u64 v[136:137], s[8:9], 0, v[136:137]
	s_waitcnt vmcnt(12)
	v_mov_b32_e32 v112, v244
	v_mov_b32_e32 v116, v245
	v_pk_mul_f32 v[136:137], v[126:127], v[112:113] op_sel_hi:[1,0]
	v_pk_mul_f32 v[138:139], v[126:127], v[116:117] op_sel:[1,0] op_sel_hi:[0,0]
	v_pk_fma_f32 v[126:127], v[126:127], v[112:113], v[138:139] op_sel_hi:[1,0,1] neg_lo:[0,0,1] neg_hi:[0,0,1]
	s_nop 0
	v_add_f32_e32 v126, v136, v138
.LBB0_1038:
	s_or_b64 exec, exec, s[48:49]
	s_cbranch_vccz .Lq_pf_skip5
	global_load_dword v244, v251, s[56:57] offset:384
	global_load_dword v245, v251, s[72:73] offset:384
.Lq_pf_skip5:
	v_cvt_pk_bf16_f32 v112, v127, s0
	v_mov_b32_e32 v141, v140
	ds_write_b16 v150, v112 offset:32
	v_cvt_pk_bf16_f32 v112, v126, s0
	v_mov_b32_e32 v116, v113
	ds_write_b16 v151, v112 offset:96
	v_pk_mul_f32 v[112:113], v[116:117], v[140:141]
	s_and_saveexec_b64 s[48:49], vcc
	s_cbranch_execz .LBB0_1040
	v_lshlrev_b64 v[116:117], 7, v[120:121]
	v_lshl_or_b32 v116, v132, 2, v116
	v_lshl_add_u64 v[120:121], s[6:7], 0, v[116:117]
	v_lshl_add_u64 v[116:117], s[8:9], 0, v[116:117]
	s_waitcnt vmcnt(12)
	v_mov_b32_e32 v120, v246
	s_nop 0
	v_mov_b32_e32 v116, v247
	v_pk_mul_f32 v[126:127], v[112:113], v[120:121] op_sel_hi:[1,0]
	v_pk_mul_f32 v[116:117], v[112:113], v[116:117] op_sel:[1,0] op_sel_hi:[0,0]
	v_pk_fma_f32 v[112:113], v[112:113], v[120:121], v[116:117] op_sel_hi:[1,0,1] neg_lo:[0,0,1] neg_hi:[0,0,1]
	s_nop 0
	v_add_f32_e32 v112, v126, v116
.LBB0_1040:
	s_or_b64 exec, exec, s[48:49]
	s_cbranch_vccz .Lq_pf_skip6
	global_load_dword v246, v251, s[56:57] offset:64
	global_load_dword v247, v251, s[72:73] offset:64
.Lq_pf_skip6:
	v_cvt_pk_bf16_f32 v113, v113, s0
	v_cvt_pk_bf16_f32 v112, v112, s0
	v_mov_b32_e32 v143, v142
	ds_write_b16 v151, v113 offset:176
	ds_write_b16 v152, v112 offset:96
	v_mov_b32_e32 v112, v114
	v_mov_b32_e32 v113, v118
	v_pk_mul_f32 v[112:113], v[112:113], v[142:143]
	s_and_saveexec_b64 s[48:49], vcc
	s_cbranch_execz .LBB0_1042
	v_lshlrev_b64 v[116:117], 7, v[124:125]
	v_lshl_or_b32 v116, v132, 2, v116
	v_lshl_add_u64 v[120:121], s[6:7], 0, v[116:117]
	v_lshl_add_u64 v[116:117], s[8:9], 0, v[116:117]
	s_waitcnt vmcnt(12)
	v_mov_b32_e32 v114, v248
	s_nop 0
	v_mov_b32_e32 v116, v249
	v_pk_mul_f32 v[120:121], v[112:113], v[114:115] op_sel_hi:[1,0]
	v_pk_mul_f32 v[116:117], v[112:113], v[116:117] op_sel:[1,0] op_sel_hi:[0,0]
	v_pk_fma_f32 v[112:113], v[112:113], v[114:115], v[116:117] op_sel_hi:[1,0,1] neg_lo:[0,0,1] neg_hi:[0,0,1]
	s_nop 0
	v_add_f32_e32 v112, v120, v116
.LBB0_1042:
	s_or_b64 exec, exec, s[48:49]
	s_cbranch_vccz .Lq_pf_skip7
	global_load_dword v248, v251, s[56:57] offset:192
	global_load_dword v249, v251, s[72:73] offset:192
.Lq_pf_skip7:
	v_mov_b32_e32 v145, v144
	v_cvt_pk_bf16_f32 v113, v113, s0
	v_cvt_pk_bf16_f32 v112, v112, s0
	v_mov_b32_e32 v118, v115
	ds_write_b16 v153, v113 offset:32
	ds_write_b16 v154, v112 offset:96
	v_pk_mul_f32 v[112:113], v[118:119], v[144:145]
	s_and_saveexec_b64 s[48:49], vcc
	s_cbranch_execz .LBB0_1044
	v_lshlrev_b64 v[114:115], 7, v[122:123]
	v_lshl_or_b32 v114, v132, 2, v114
	v_lshl_add_u64 v[116:117], s[6:7], 0, v[114:115]
	v_lshl_add_u64 v[114:115], s[8:9], 0, v[114:115]
	s_waitcnt vmcnt(12)
	v_mov_b32_e32 v116, v236
	s_nop 0
	v_mov_b32_e32 v114, v237
	v_pk_mul_f32 v[118:119], v[112:113], v[116:117] op_sel_hi:[1,0]
	v_pk_mul_f32 v[114:115], v[112:113], v[114:115] op_sel:[1,0] op_sel_hi:[0,0]
	v_pk_fma_f32 v[112:113], v[112:113], v[116:117], v[114:115] op_sel_hi:[1,0,1] neg_lo:[0,0,1] neg_hi:[0,0,1]
	s_nop 0
	v_add_f32_e32 v112, v118, v114
.LBB0_1044:
	s_or_b64 exec, exec, s[48:49]
	s_cbranch_vccz .Lq_pf_skip8
	global_load_dword v236, v251, s[56:57] offset:320
	global_load_dword v237, v251, s[72:73] offset:320
.Lq_pf_skip8:
	v_cvt_pk_bf16_f32 v113, v113, s0
	v_cvt_pk_bf16_f32 v112, v112, s0
	ds_write_b16 v155, v113 offset:32
	ds_write_b16 v156, v112 offset:96
	ds_read_b32 v114, v149 offset:64
	v_mov_b32_e32 v116, v104
	v_or_b32_e32 v104, 16, v133
	v_mov_b32_e32 v117, v108
	v_or_b32_e32 v112, v231, v104
	s_waitcnt lgkmcnt(0)
	v_pk_mul_f32 v[118:119], v[116:117], v[114:115] op_sel_hi:[1,0]
	v_ashrrev_i32_e32 v113, 31, v112
	s_and_saveexec_b64 s[48:49], vcc
	s_cbranch_execz .LBB0_1046
	v_lshlrev_b64 v[116:117], 7, v[112:113]
	v_lshl_or_b32 v116, v130, 2, v116
	v_lshl_add_u64 v[120:121], s[6:7], 0, v[116:117]
	v_lshl_add_u64 v[116:117], s[8:9], 0, v[116:117]
	s_waitcnt vmcnt(12)
	v_mov_b32_e32 v104, v238
	v_mov_b32_e32 v108, v239
	v_pk_mul_f32 v[116:117], v[118:119], v[104:105] op_sel_hi:[1,0]
	v_pk_mul_f32 v[120:121], v[118:119], v[108:109] op_sel:[1,0] op_sel_hi:[0,0]
	v_pk_fma_f32 v[118:119], v[118:119], v[104:105], v[120:121] op_sel_hi:[1,0,1] neg_lo:[0,0,1] neg_hi:[0,0,1]
	s_nop 0
	v_add_f32_e32 v118, v116, v120
.LBB0_1046:
	s_or_b64 exec, exec, s[48:49]
	s_cbranch_vccz .Lq_pf_skip9
	global_load_dword v238, v251, s[56:57] offset:448
	global_load_dword v239, v251, s[72:73] offset:448
.Lq_pf_skip9:
	ds_read_b32 v116, v149 offset:68
	v_cvt_pk_bf16_f32 v104, v119, s0
	ds_write_b16 v157, v104
	v_cvt_pk_bf16_f32 v104, v118, s0
	ds_write_b16 v158, v104 offset:64
	v_or_b32_e32 v104, 17, v133
	v_mov_b32_e32 v108, v105
	v_or_b32_e32 v104, v231, v104
	s_waitcnt lgkmcnt(2)
	v_pk_mul_f32 v[108:109], v[108:109], v[116:117] op_sel_hi:[1,0]
	v_ashrrev_i32_e32 v105, 31, v104
	s_and_saveexec_b64 s[48:49], vcc
	s_cbranch_execz .LBB0_1048
	v_lshlrev_b64 v[118:119], 7, v[104:105]
	v_lshl_or_b32 v118, v130, 2, v118
	v_lshl_add_u64 v[120:121], s[6:7], 0, v[118:119]
	v_lshl_add_u64 v[118:119], s[8:9], 0, v[118:119]
	s_waitcnt vmcnt(12)
	v_mov_b32_e32 v120, v240
	s_nop 0
	v_mov_b32_e32 v118, v241
	v_pk_mul_f32 v[122:123], v[108:109], v[120:121] op_sel_hi:[1,0]
	v_pk_mul_f32 v[118:119], v[108:109], v[118:119] op_sel:[1,0] op_sel_hi:[0,0]
	v_pk_fma_f32 v[108:109], v[108:109], v[120:121], v[118:119] op_sel_hi:[1,0,1] neg_lo:[0,0,1] neg_hi:[0,0,1]
	s_nop 0
	v_add_f32_e32 v108, v122, v118
.LBB0_1048:
	s_or_b64 exec, exec, s[48:49]
	s_cbranch_vccz .Lq_pf_skip10
	s_add_u32 s56, s56, 0x800
	s_addc_u32 s57, s57, 0
	s_add_u32 s72, s72, 0x800
	s_addc_u32 s73, s73, 0
	global_load_dword v240, v251, s[56:57]
	global_load_dword v241, v251, s[72:73]
.Lq_pf_skip10:
	ds_read_b32 v118, v149 offset:72
	v_cvt_pk_bf16_f32 v109, v109, s0
	v_cvt_pk_bf16_f32 v108, v108, s0
	ds_write_b16 v159, v109
	ds_write_b16 v160, v108 offset:64
	v_mov_b32_e32 v108, v106
	v_mov_b32_e32 v109, v110
	v_or_b32_e32 v106, 18, v133
	s_waitcnt lgkmcnt(2)
	v_pk_mul_f32 v[122:123], v[108:109], v[118:119] op_sel_hi:[1,0]
	v_or_b32_e32 v108, v231, v106
	v_ashrrev_i32_e32 v109, 31, v108
	s_and_saveexec_b64 s[48:49], vcc
	s_cbranch_execz .LBB0_1050
	v_lshlrev_b64 v[120:121], 7, v[108:109]
	v_lshl_or_b32 v120, v130, 2, v120
	v_lshl_add_u64 v[124:125], s[6:7], 0, v[120:121]
	v_lshl_add_u64 v[120:121], s[8:9], 0, v[120:121]
	s_waitcnt vmcnt(12)
	v_mov_b32_e32 v106, v242
	v_mov_b32_e32 v110, v243
	v_pk_mul_f32 v[120:121], v[122:123], v[106:107] op_sel_hi:[1,0]
	v_pk_mul_f32 v[124:125], v[122:123], v[110:111] op_sel:[1,0] op_sel_hi:[0,0]
	v_pk_fma_f32 v[122:123], v[122:123], v[106:107], v[124:125] op_sel_hi:[1,0,1] neg_lo:[0,0,1] neg_hi:[0,0,1]
	s_nop 0
	v_add_f32_e32 v122, v120, v124
.LBB0_1050:
	s_or_b64 exec, exec, s[48:49]
	s_cbranch_vccz .Lq_pf_skip11
	global_load_dword v242, v251, s[56:57] offset:128
	global_load_dword v243, v251, s[72:73] offset:128
.Lq_pf_skip11:
	ds_read_b32 v120, v149 offset:76
	v_cvt_pk_bf16_f32 v106, v123, s0
	ds_write_b16 v161, v106
	v_cvt_pk_bf16_f32 v106, v122, s0
	ds_write_b16 v162, v106 offset:64
	v_or_b32_e32 v106, 19, v133
	v_mov_b32_e32 v110, v107
	v_or_b32_e32 v106, v231, v106
	s_waitcnt lgkmcnt(2)
	v_pk_mul_f32 v[110:111], v[110:111], v[120:121] op_sel_hi:[1,0]
	v_ashrrev_i32_e32 v107, 31, v106
	s_and_saveexec_b64 s[48:49], vcc
	s_cbranch_execz .LBB0_1052
	v_lshlrev_b64 v[122:123], 7, v[106:107]
	v_lshl_or_b32 v122, v130, 2, v122
	v_lshl_add_u64 v[124:125], s[6:7], 0, v[122:123]
	v_lshl_add_u64 v[122:123], s[8:9], 0, v[122:123]
	s_waitcnt vmcnt(12)
	v_mov_b32_e32 v124, v244
	s_nop 0
	v_mov_b32_e32 v122, v245
	v_pk_mul_f32 v[126:127], v[110:111], v[124:125] op_sel_hi:[1,0]
	v_pk_mul_f32 v[122:123], v[110:111], v[122:123] op_sel:[1,0] op_sel_hi:[0,0]
	v_pk_fma_f32 v[110:111], v[110:111], v[124:125], v[122:123] op_sel_hi:[1,0,1] neg_lo:[0,0,1] neg_hi:[0,0,1]
	s_nop 0
	v_add_f32_e32 v110, v126, v122
.LBB0_1052:
	s_or_b64 exec, exec, s[48:49]
	s_cbranch_vccz .Lq_pf_skip12
	global_load_dword v244, v251, s[56:57] offset:256
	global_load_dword v245, v251, s[72:73] offset:256
.Lq_pf_skip12:
	v_cvt_pk_bf16_f32 v111, v111, s0
	v_cvt_pk_bf16_f32 v110, v110, s0
	v_mov_b32_e32 v115, v114
	ds_write_b16 v163, v111
	ds_write_b16 v164, v110 offset:64
	v_mov_b32_e32 v110, v96
	v_mov_b32_e32 v111, v100
	v_pk_mul_f32 v[110:111], v[110:111], v[114:115]
	s_and_saveexec_b64 s[48:49], vcc
	s_cbranch_execz .LBB0_1054
	v_lshlrev_b64 v[112:113], 7, v[112:113]
	v_lshl_or_b32 v112, v132, 2, v112
	v_lshl_add_u64 v[114:115], s[6:7], 0, v[112:113]
	v_lshl_add_u64 v[112:113], s[8:9], 0, v[112:113]
	s_waitcnt vmcnt(12)
	v_mov_b32_e32 v96, v246
	v_mov_b32_e32 v100, v247
	v_pk_mul_f32 v[112:113], v[110:111], v[96:97] op_sel_hi:[1,0]
	v_pk_mul_f32 v[114:115], v[110:111], v[100:101] op_sel:[1,0] op_sel_hi:[0,0]
	v_pk_fma_f32 v[110:111], v[110:111], v[96:97], v[114:115] op_sel_hi:[1,0,1] neg_lo:[0,0,1] neg_hi:[0,0,1]
	s_nop 0
	v_add_f32_e32 v110, v112, v114
.LBB0_1054:
	s_or_b64 exec, exec, s[48:49]
	s_cbranch_vccz .Lq_pf_skip13
	global_load_dword v246, v251, s[56:57] offset:384
	global_load_dword v247, v251, s[72:73] offset:384
.Lq_pf_skip13:
	v_cvt_pk_bf16_f32 v96, v111, s0
	v_mov_b32_e32 v117, v116
	ds_write_b16 v157, v96 offset:32
	v_cvt_pk_bf16_f32 v96, v110, s0
	v_mov_b32_e32 v100, v97
	ds_write_b16 v158, v96 offset:96
	v_pk_mul_f32 v[96:97], v[100:101], v[116:117]
	s_and_saveexec_b64 s[48:49], vcc
	s_cbranch_execz .LBB0_1056
	v_lshlrev_b64 v[100:101], 7, v[104:105]
	v_lshl_or_b32 v100, v132, 2, v100
	v_lshl_add_u64 v[104:105], s[6:7], 0, v[100:101]
	v_lshl_add_u64 v[100:101], s[8:9], 0, v[100:101]
	s_waitcnt vmcnt(12)
	v_mov_b32_e32 v104, v248
	s_nop 0
	v_mov_b32_e32 v100, v249
	v_pk_mul_f32 v[110:111], v[96:97], v[104:105] op_sel_hi:[1,0]
	v_pk_mul_f32 v[100:101], v[96:97], v[100:101] op_sel:[1,0] op_sel_hi:[0,0]
	v_pk_fma_f32 v[96:97], v[96:97], v[104:105], v[100:101] op_sel_hi:[1,0,1] neg_lo:[0,0,1] neg_hi:[0,0,1]
	s_nop 0
	v_add_f32_e32 v96, v110, v100
.LBB0_1056:
	s_or_b64 exec, exec, s[48:49]
	s_cbranch_vccz .Lq_pf_skip14
	global_load_dword v248, v251, s[56:57] offset:64
	global_load_dword v249, v251, s[72:73] offset:64
.Lq_pf_skip14:
	v_cvt_pk_bf16_f32 v97, v97, s0
	v_cvt_pk_bf16_f32 v96, v96, s0
	v_mov_b32_e32 v119, v118
	ds_write_b16 v159, v97 offset:32
	ds_write_b16 v160, v96 offset:96
	v_mov_b32_e32 v96, v98
	v_mov_b32_e32 v97, v102
	v_pk_mul_f32 v[96:97], v[96:97], v[118:119]
	s_and_saveexec_b64 s[48:49], vcc
	s_cbranch_execz .LBB0_1058
	v_lshlrev_b64 v[100:101], 7, v[108:109]
	v_lshl_or_b32 v100, v132, 2, v100
	v_lshl_add_u64 v[104:105], s[6:7], 0, v[100:101]
	v_lshl_add_u64 v[100:101], s[8:9], 0, v[100:101]
	s_waitcnt vmcnt(12)
	v_mov_b32_e32 v98, v236
	s_nop 0
	v_mov_b32_e32 v100, v237
	v_pk_mul_f32 v[104:105], v[96:97], v[98:99] op_sel_hi:[1,0]
	v_pk_mul_f32 v[100:101], v[96:97], v[100:101] op_sel:[1,0] op_sel_hi:[0,0]
	v_pk_fma_f32 v[96:97], v[96:97], v[98:99], v[100:101] op_sel_hi:[1,0,1] neg_lo:[0,0,1] neg_hi:[0,0,1]
	s_nop 0
	v_add_f32_e32 v96, v104, v100
.LBB0_1058:
	s_or_b64 exec, exec, s[48:49]
	s_cbranch_vccz .Lq_pf_skip15
	global_load_dword v236, v251, s[56:57] offset:192
	global_load_dword v237, v251, s[72:73] offset:192
.Lq_pf_skip15:
	v_mov_b32_e32 v121, v120
	v_cvt_pk_bf16_f32 v97, v97, s0
	v_cvt_pk_bf16_f32 v96, v96, s0
	v_mov_b32_e32 v102, v99
	ds_write_b16 v161, v97 offset:32
	ds_write_b16 v162, v96 offset:96
	v_pk_mul_f32 v[96:97], v[102:103], v[120:121]
	s_and_saveexec_b64 s[48:49], vcc
	s_cbranch_execz .LBB0_1060
	v_lshlrev_b64 v[98:99], 7, v[106:107]
	v_lshl_or_b32 v98, v132, 2, v98
	v_lshl_add_u64 v[100:101], s[6:7], 0, v[98:99]
	v_lshl_add_u64 v[98:99], s[8:9], 0, v[98:99]
	s_waitcnt vmcnt(12)
	v_mov_b32_e32 v100, v238
	s_nop 0
	v_mov_b32_e32 v98, v239
	v_pk_mul_f32 v[102:103], v[96:97], v[100:101] op_sel_hi:[1,0]
	v_pk_mul_f32 v[98:99], v[96:97], v[98:99] op_sel:[1,0] op_sel_hi:[0,0]
	v_pk_fma_f32 v[96:97], v[96:97], v[100:101], v[98:99] op_sel_hi:[1,0,1] neg_lo:[0,0,1] neg_hi:[0,0,1]
	s_nop 0
	v_add_f32_e32 v96, v102, v98
.LBB0_1060:
	s_or_b64 exec, exec, s[48:49]
	s_cbranch_vccz .Lq_pf_skip16
	global_load_dword v238, v251, s[56:57] offset:320
	global_load_dword v239, v251, s[72:73] offset:320
.Lq_pf_skip16:
	v_cvt_pk_bf16_f32 v97, v97, s0
	v_cvt_pk_bf16_f32 v96, v96, s0
	ds_write_b16 v163, v97 offset:32
	ds_write_b16 v164, v96 offset:96
	ds_read_b32 v98, v149 offset:128
	v_mov_b32_e32 v100, v88
	v_or_b32_e32 v88, 32, v133
	v_mov_b32_e32 v101, v92
	v_or_b32_e32 v96, v231, v88
	s_waitcnt lgkmcnt(0)
	v_pk_mul_f32 v[102:103], v[100:101], v[98:99] op_sel_hi:[1,0]
	v_ashrrev_i32_e32 v97, 31, v96
	s_and_saveexec_b64 s[48:49], vcc
	s_cbranch_execz .LBB0_1062
	v_lshlrev_b64 v[100:101], 7, v[96:97]
	v_lshl_or_b32 v100, v130, 2, v100
	v_lshl_add_u64 v[104:105], s[6:7], 0, v[100:101]
	v_lshl_add_u64 v[100:101], s[8:9], 0, v[100:101]
	s_waitcnt vmcnt(12)
	v_mov_b32_e32 v88, v240
	v_mov_b32_e32 v92, v241
	v_pk_mul_f32 v[100:101], v[102:103], v[88:89] op_sel_hi:[1,0]
	v_pk_mul_f32 v[104:105], v[102:103], v[92:93] op_sel:[1,0] op_sel_hi:[0,0]
	v_pk_fma_f32 v[102:103], v[102:103], v[88:89], v[104:105] op_sel_hi:[1,0,1] neg_lo:[0,0,1] neg_hi:[0,0,1]
	s_nop 0
	v_add_f32_e32 v102, v100, v104
.LBB0_1062:
	s_or_b64 exec, exec, s[48:49]
	s_cbranch_vccz .Lq_pf_skip17
	global_load_dword v240, v251, s[56:57] offset:448
	global_load_dword v241, v251, s[72:73] offset:448
.Lq_pf_skip17:
	ds_read_b32 v100, v149 offset:132
	v_cvt_pk_bf16_f32 v88, v103, s0
	ds_write_b16 v165, v88
	v_cvt_pk_bf16_f32 v88, v102, s0
	ds_write_b16 v166, v88 offset:64
	v_or_b32_e32 v88, 33, v133
	v_mov_b32_e32 v92, v89
	v_or_b32_e32 v88, v231, v88
	s_waitcnt lgkmcnt(2)
	v_pk_mul_f32 v[92:93], v[92:93], v[100:101] op_sel_hi:[1,0]
	v_ashrrev_i32_e32 v89, 31, v88
	s_and_saveexec_b64 s[48:49], vcc
	s_cbranch_execz .LBB0_1064
	v_lshlrev_b64 v[102:103], 7, v[88:89]
	v_lshl_or_b32 v102, v130, 2, v102
	v_lshl_add_u64 v[104:105], s[6:7], 0, v[102:103]
	v_lshl_add_u64 v[102:103], s[8:9], 0, v[102:103]
	s_waitcnt vmcnt(12)
	v_mov_b32_e32 v104, v242
	s_nop 0
	v_mov_b32_e32 v102, v243
	v_pk_mul_f32 v[106:107], v[92:93], v[104:105] op_sel_hi:[1,0]
	v_pk_mul_f32 v[102:103], v[92:93], v[102:103] op_sel:[1,0] op_sel_hi:[0,0]
	v_pk_fma_f32 v[92:93], v[92:93], v[104:105], v[102:103] op_sel_hi:[1,0,1] neg_lo:[0,0,1] neg_hi:[0,0,1]
	s_nop 0
	v_add_f32_e32 v92, v106, v102
.LBB0_1064:
	s_or_b64 exec, exec, s[48:49]
	s_cbranch_vccz .Lq_pf_skip18
	s_add_u32 s56, s56, 0x800
	s_addc_u32 s57, s57, 0
	s_add_u32 s72, s72, 0x800
	s_addc_u32 s73, s73, 0
	global_load_dword v242, v251, s[56:57]
	global_load_dword v243, v251, s[72:73]
.Lq_pf_skip18:
	ds_read_b32 v102, v149 offset:136
	v_cvt_pk_bf16_f32 v93, v93, s0
	v_cvt_pk_bf16_f32 v92, v92, s0
	ds_write_b16 v167, v93
	ds_write_b16 v168, v92 offset:64
	v_mov_b32_e32 v92, v90
	v_mov_b32_e32 v93, v94
	v_or_b32_e32 v90, 34, v133
	s_waitcnt lgkmcnt(2)
	v_pk_mul_f32 v[106:107], v[92:93], v[102:103] op_sel_hi:[1,0]
	v_or_b32_e32 v92, v231, v90
	v_ashrrev_i32_e32 v93, 31, v92
	s_and_saveexec_b64 s[48:49], vcc
	s_cbranch_execz .LBB0_1066
	v_lshlrev_b64 v[104:105], 7, v[92:93]
	v_lshl_or_b32 v104, v130, 2, v104
	v_lshl_add_u64 v[108:109], s[6:7], 0, v[104:105]
	v_lshl_add_u64 v[104:105], s[8:9], 0, v[104:105]
	s_waitcnt vmcnt(12)
	v_mov_b32_e32 v90, v244
	v_mov_b32_e32 v94, v245
	v_pk_mul_f32 v[104:105], v[106:107], v[90:91] op_sel_hi:[1,0]
	v_pk_mul_f32 v[108:109], v[106:107], v[94:95] op_sel:[1,0] op_sel_hi:[0,0]
	v_pk_fma_f32 v[106:107], v[106:107], v[90:91], v[108:109] op_sel_hi:[1,0,1] neg_lo:[0,0,1] neg_hi:[0,0,1]
	s_nop 0
	v_add_f32_e32 v106, v104, v108
.LBB0_1066:
	s_or_b64 exec, exec, s[48:49]
	s_cbranch_vccz .Lq_pf_skip19
	global_load_dword v244, v251, s[56:57] offset:128
	global_load_dword v245, v251, s[72:73] offset:128
.Lq_pf_skip19:
	ds_read_b32 v104, v149 offset:140
	v_cvt_pk_bf16_f32 v90, v107, s0
	ds_write_b16 v169, v90
	v_cvt_pk_bf16_f32 v90, v106, s0
	ds_write_b16 v170, v90 offset:64
	v_or_b32_e32 v90, 35, v133
	v_mov_b32_e32 v94, v91
	v_or_b32_e32 v90, v231, v90
	s_waitcnt lgkmcnt(2)
	v_pk_mul_f32 v[94:95], v[94:95], v[104:105] op_sel_hi:[1,0]
	v_ashrrev_i32_e32 v91, 31, v90
	s_and_saveexec_b64 s[48:49], vcc
	s_cbranch_execz .LBB0_1068
	v_lshlrev_b64 v[106:107], 7, v[90:91]
	v_lshl_or_b32 v106, v130, 2, v106
	v_lshl_add_u64 v[108:109], s[6:7], 0, v[106:107]
	v_lshl_add_u64 v[106:107], s[8:9], 0, v[106:107]
	s_waitcnt vmcnt(12)
	v_mov_b32_e32 v108, v246
	s_nop 0
	v_mov_b32_e32 v106, v247
	v_pk_mul_f32 v[110:111], v[94:95], v[108:109] op_sel_hi:[1,0]
	v_pk_mul_f32 v[106:107], v[94:95], v[106:107] op_sel:[1,0] op_sel_hi:[0,0]
	v_pk_fma_f32 v[94:95], v[94:95], v[108:109], v[106:107] op_sel_hi:[1,0,1] neg_lo:[0,0,1] neg_hi:[0,0,1]
	s_nop 0
	v_add_f32_e32 v94, v110, v106
.LBB0_1068:
	s_or_b64 exec, exec, s[48:49]
	s_cbranch_vccz .Lq_pf_skip20
	global_load_dword v246, v251, s[56:57] offset:256
	global_load_dword v247, v251, s[72:73] offset:256
.Lq_pf_skip20:
	v_cvt_pk_bf16_f32 v95, v95, s0
	v_cvt_pk_bf16_f32 v94, v94, s0
	v_mov_b32_e32 v99, v98
	ds_write_b16 v171, v95
	ds_write_b16 v172, v94 offset:64
	v_mov_b32_e32 v94, v80
	v_mov_b32_e32 v95, v84
	v_pk_mul_f32 v[94:95], v[94:95], v[98:99]
	s_and_saveexec_b64 s[48:49], vcc
	s_cbranch_execz .LBB0_1070
	v_lshlrev_b64 v[96:97], 7, v[96:97]
	v_lshl_or_b32 v96, v132, 2, v96
	v_lshl_add_u64 v[98:99], s[6:7], 0, v[96:97]
	v_lshl_add_u64 v[96:97], s[8:9], 0, v[96:97]
	s_waitcnt vmcnt(12)
	v_mov_b32_e32 v80, v248
	v_mov_b32_e32 v84, v249
	v_pk_mul_f32 v[96:97], v[94:95], v[80:81] op_sel_hi:[1,0]
	v_pk_mul_f32 v[98:99], v[94:95], v[84:85] op_sel:[1,0] op_sel_hi:[0,0]
	v_pk_fma_f32 v[94:95], v[94:95], v[80:81], v[98:99] op_sel_hi:[1,0,1] neg_lo:[0,0,1] neg_hi:[0,0,1]
	s_nop 0
	v_add_f32_e32 v94, v96, v98
.LBB0_1070:
	s_or_b64 exec, exec, s[48:49]
	s_cbranch_vccz .Lq_pf_skip21
	global_load_dword v248, v251, s[56:57] offset:384
	global_load_dword v249, v251, s[72:73] offset:384
.Lq_pf_skip21:
	v_cvt_pk_bf16_f32 v80, v95, s0
	v_mov_b32_e32 v101, v100
	ds_write_b16 v165, v80 offset:32
	v_cvt_pk_bf16_f32 v80, v94, s0
	v_mov_b32_e32 v84, v81
	ds_write_b16 v166, v80 offset:96
	v_pk_mul_f32 v[80:81], v[84:85], v[100:101]
	s_and_saveexec_b64 s[48:49], vcc
	s_cbranch_execz .LBB0_1072
	v_lshlrev_b64 v[84:85], 7, v[88:89]
	v_lshl_or_b32 v84, v132, 2, v84
	v_lshl_add_u64 v[88:89], s[6:7], 0, v[84:85]
	v_lshl_add_u64 v[84:85], s[8:9], 0, v[84:85]
	s_waitcnt vmcnt(12)
	v_mov_b32_e32 v88, v236
	s_nop 0
	v_mov_b32_e32 v84, v237
	v_pk_mul_f32 v[94:95], v[80:81], v[88:89] op_sel_hi:[1,0]
	v_pk_mul_f32 v[84:85], v[80:81], v[84:85] op_sel:[1,0] op_sel_hi:[0,0]
	v_pk_fma_f32 v[80:81], v[80:81], v[88:89], v[84:85] op_sel_hi:[1,0,1] neg_lo:[0,0,1] neg_hi:[0,0,1]
	s_nop 0
	v_add_f32_e32 v80, v94, v84
.LBB0_1072:
	s_or_b64 exec, exec, s[48:49]
	s_cbranch_vccz .Lq_pf_skip22
	global_load_dword v236, v251, s[56:57] offset:64
	global_load_dword v237, v251, s[72:73] offset:64
.Lq_pf_skip22:
	v_cvt_pk_bf16_f32 v81, v81, s0
	v_cvt_pk_bf16_f32 v80, v80, s0
	v_mov_b32_e32 v103, v102
	ds_write_b16 v167, v81 offset:32
	ds_write_b16 v168, v80 offset:96
	v_mov_b32_e32 v80, v82
	v_mov_b32_e32 v81, v86
	v_pk_mul_f32 v[80:81], v[80:81], v[102:103]
	s_and_saveexec_b64 s[48:49], vcc
	s_cbranch_execz .LBB0_1074
	v_lshlrev_b64 v[84:85], 7, v[92:93]
	v_lshl_or_b32 v84, v132, 2, v84
	v_lshl_add_u64 v[88:89], s[6:7], 0, v[84:85]
	v_lshl_add_u64 v[84:85], s[8:9], 0, v[84:85]
	s_waitcnt vmcnt(12)
	v_mov_b32_e32 v82, v238
	s_nop 0
	v_mov_b32_e32 v84, v239
	v_pk_mul_f32 v[88:89], v[80:81], v[82:83] op_sel_hi:[1,0]
	v_pk_mul_f32 v[84:85], v[80:81], v[84:85] op_sel:[1,0] op_sel_hi:[0,0]
	v_pk_fma_f32 v[80:81], v[80:81], v[82:83], v[84:85] op_sel_hi:[1,0,1] neg_lo:[0,0,1] neg_hi:[0,0,1]
	s_nop 0
	v_add_f32_e32 v80, v88, v84
.LBB0_1074:
	s_or_b64 exec, exec, s[48:49]
	s_cbranch_vccz .Lq_pf_skip23
	global_load_dword v238, v251, s[56:57] offset:192
	global_load_dword v239, v251, s[72:73] offset:192
.Lq_pf_skip23:
	v_mov_b32_e32 v105, v104
	v_cvt_pk_bf16_f32 v81, v81, s0
	v_cvt_pk_bf16_f32 v80, v80, s0
	v_mov_b32_e32 v86, v83
	ds_write_b16 v169, v81 offset:32
	ds_write_b16 v170, v80 offset:96
	v_pk_mul_f32 v[80:81], v[86:87], v[104:105]
	s_and_saveexec_b64 s[48:49], vcc
	s_cbranch_execz .LBB0_1076
	v_lshlrev_b64 v[82:83], 7, v[90:91]
	v_lshl_or_b32 v82, v132, 2, v82
	v_lshl_add_u64 v[84:85], s[6:7], 0, v[82:83]
	v_lshl_add_u64 v[82:83], s[8:9], 0, v[82:83]
	s_waitcnt vmcnt(12)
	v_mov_b32_e32 v84, v240
	s_nop 0
	v_mov_b32_e32 v82, v241
	v_pk_mul_f32 v[86:87], v[80:81], v[84:85] op_sel_hi:[1,0]
	v_pk_mul_f32 v[82:83], v[80:81], v[82:83] op_sel:[1,0] op_sel_hi:[0,0]
	v_pk_fma_f32 v[80:81], v[80:81], v[84:85], v[82:83] op_sel_hi:[1,0,1] neg_lo:[0,0,1] neg_hi:[0,0,1]
	s_nop 0
	v_add_f32_e32 v80, v86, v82
.LBB0_1076:
	s_or_b64 exec, exec, s[48:49]
	s_cbranch_vccz .Lq_pf_skip24
	global_load_dword v240, v251, s[56:57] offset:320
	global_load_dword v241, v251, s[72:73] offset:320
.Lq_pf_skip24:
	v_cvt_pk_bf16_f32 v81, v81, s0
	v_cvt_pk_bf16_f32 v80, v80, s0
	ds_write_b16 v171, v81 offset:32
	ds_write_b16 v172, v80 offset:96
	ds_read_b32 v82, v149 offset:192
	v_mov_b32_e32 v84, v72
	v_or_b32_e32 v72, 48, v133
	v_mov_b32_e32 v85, v76
	v_or_b32_e32 v80, v231, v72
	s_waitcnt lgkmcnt(0)
	v_pk_mul_f32 v[86:87], v[84:85], v[82:83] op_sel_hi:[1,0]
	v_ashrrev_i32_e32 v81, 31, v80
	s_and_saveexec_b64 s[48:49], vcc
	s_cbranch_execz .LBB0_1078
	v_lshlrev_b64 v[84:85], 7, v[80:81]
	v_lshl_or_b32 v84, v130, 2, v84
	v_lshl_add_u64 v[88:89], s[6:7], 0, v[84:85]
	v_lshl_add_u64 v[84:85], s[8:9], 0, v[84:85]
	s_waitcnt vmcnt(12)
	v_mov_b32_e32 v72, v242
	v_mov_b32_e32 v76, v243
	v_pk_mul_f32 v[84:85], v[86:87], v[72:73] op_sel_hi:[1,0]
	v_pk_mul_f32 v[88:89], v[86:87], v[76:77] op_sel:[1,0] op_sel_hi:[0,0]
	v_pk_fma_f32 v[86:87], v[86:87], v[72:73], v[88:89] op_sel_hi:[1,0,1] neg_lo:[0,0,1] neg_hi:[0,0,1]
	s_nop 0
	v_add_f32_e32 v86, v84, v88
.LBB0_1078:
	s_or_b64 exec, exec, s[48:49]
	s_cbranch_vccz .Lq_pf_skip25
	global_load_dword v242, v251, s[56:57] offset:448
	global_load_dword v243, v251, s[72:73] offset:448
.Lq_pf_skip25:
	ds_read_b32 v84, v149 offset:196
	v_cvt_pk_bf16_f32 v72, v87, s0
	ds_write_b16 v173, v72
	v_cvt_pk_bf16_f32 v72, v86, s0
	ds_write_b16 v174, v72 offset:64
	v_or_b32_e32 v72, 49, v133
	v_mov_b32_e32 v76, v73
	v_or_b32_e32 v72, v231, v72
	s_waitcnt lgkmcnt(2)
	v_pk_mul_f32 v[76:77], v[76:77], v[84:85] op_sel_hi:[1,0]
	v_ashrrev_i32_e32 v73, 31, v72
	s_and_saveexec_b64 s[48:49], vcc
	s_cbranch_execz .LBB0_1080
	v_lshlrev_b64 v[86:87], 7, v[72:73]
	v_lshl_or_b32 v86, v130, 2, v86
	v_lshl_add_u64 v[88:89], s[6:7], 0, v[86:87]
	v_lshl_add_u64 v[86:87], s[8:9], 0, v[86:87]
	s_waitcnt vmcnt(12)
	v_mov_b32_e32 v88, v244
	s_nop 0
	v_mov_b32_e32 v86, v245
	v_pk_mul_f32 v[90:91], v[76:77], v[88:89] op_sel_hi:[1,0]
	v_pk_mul_f32 v[86:87], v[76:77], v[86:87] op_sel:[1,0] op_sel_hi:[0,0]
	v_pk_fma_f32 v[76:77], v[76:77], v[88:89], v[86:87] op_sel_hi:[1,0,1] neg_lo:[0,0,1] neg_hi:[0,0,1]
	s_nop 0
	v_add_f32_e32 v76, v90, v86
.LBB0_1080:
	s_or_b64 exec, exec, s[48:49]
	s_cbranch_vccz .Lq_pf_skip26
	s_add_u32 s56, s56, 0x800
	s_addc_u32 s57, s57, 0
	s_add_u32 s72, s72, 0x800
	s_addc_u32 s73, s73, 0
	global_load_dword v244, v251, s[56:57]
	global_load_dword v245, v251, s[72:73]
.Lq_pf_skip26:
	ds_read_b32 v86, v149 offset:200
	v_cvt_pk_bf16_f32 v77, v77, s0
	v_cvt_pk_bf16_f32 v76, v76, s0
	ds_write_b16 v175, v77
	ds_write_b16 v176, v76 offset:64
	v_mov_b32_e32 v76, v74
	v_mov_b32_e32 v77, v78
	v_or_b32_e32 v74, 50, v133
	s_waitcnt lgkmcnt(2)
	v_pk_mul_f32 v[90:91], v[76:77], v[86:87] op_sel_hi:[1,0]
	v_or_b32_e32 v76, v231, v74
	v_ashrrev_i32_e32 v77, 31, v76
	s_and_saveexec_b64 s[48:49], vcc
	s_cbranch_execz .LBB0_1082
	v_lshlrev_b64 v[88:89], 7, v[76:77]
	v_lshl_or_b32 v88, v130, 2, v88
	v_lshl_add_u64 v[92:93], s[6:7], 0, v[88:89]
	v_lshl_add_u64 v[88:89], s[8:9], 0, v[88:89]
	s_waitcnt vmcnt(12)
	v_mov_b32_e32 v74, v246
	v_mov_b32_e32 v78, v247
	v_pk_mul_f32 v[88:89], v[90:91], v[74:75] op_sel_hi:[1,0]
	v_pk_mul_f32 v[92:93], v[90:91], v[78:79] op_sel:[1,0] op_sel_hi:[0,0]
	v_pk_fma_f32 v[90:91], v[90:91], v[74:75], v[92:93] op_sel_hi:[1,0,1] neg_lo:[0,0,1] neg_hi:[0,0,1]
	s_nop 0
	v_add_f32_e32 v90, v88, v92
.LBB0_1082:
	s_or_b64 exec, exec, s[48:49]
	s_cbranch_vccz .Lq_pf_skip27
	global_load_dword v246, v251, s[56:57] offset:128
	global_load_dword v247, v251, s[72:73] offset:128
.Lq_pf_skip27:
	ds_read_b32 v88, v149 offset:204
	v_cvt_pk_bf16_f32 v74, v91, s0
	ds_write_b16 v177, v74
	v_cvt_pk_bf16_f32 v74, v90, s0
	ds_write_b16 v178, v74 offset:64
	v_or_b32_e32 v74, 51, v133
	v_mov_b32_e32 v78, v75
	v_or_b32_e32 v74, v231, v74
	s_waitcnt lgkmcnt(2)
	v_pk_mul_f32 v[78:79], v[78:79], v[88:89] op_sel_hi:[1,0]
	v_ashrrev_i32_e32 v75, 31, v74
	s_and_saveexec_b64 s[48:49], vcc
	s_cbranch_execz .LBB0_1084
	v_lshlrev_b64 v[90:91], 7, v[74:75]
	v_lshl_or_b32 v90, v130, 2, v90
	v_lshl_add_u64 v[92:93], s[6:7], 0, v[90:91]
	v_lshl_add_u64 v[90:91], s[8:9], 0, v[90:91]
	s_waitcnt vmcnt(12)
	v_mov_b32_e32 v92, v248
	s_nop 0
	v_mov_b32_e32 v90, v249
	v_pk_mul_f32 v[94:95], v[78:79], v[92:93] op_sel_hi:[1,0]
	v_pk_mul_f32 v[90:91], v[78:79], v[90:91] op_sel:[1,0] op_sel_hi:[0,0]
	v_pk_fma_f32 v[78:79], v[78:79], v[92:93], v[90:91] op_sel_hi:[1,0,1] neg_lo:[0,0,1] neg_hi:[0,0,1]
	s_nop 0
	v_add_f32_e32 v78, v94, v90
.LBB0_1084:
	s_or_b64 exec, exec, s[48:49]
	s_cbranch_vccz .Lq_pf_skip28
	global_load_dword v248, v251, s[56:57] offset:256
	global_load_dword v249, v251, s[72:73] offset:256
.Lq_pf_skip28:
	v_cvt_pk_bf16_f32 v79, v79, s0
	v_cvt_pk_bf16_f32 v78, v78, s0
	v_mov_b32_e32 v83, v82
	ds_write_b16 v179, v79
	ds_write_b16 v180, v78 offset:64
	v_mov_b32_e32 v78, v64
	v_mov_b32_e32 v79, v68
	v_pk_mul_f32 v[78:79], v[78:79], v[82:83]
	s_and_saveexec_b64 s[48:49], vcc
	s_cbranch_execz .LBB0_1086
	v_lshlrev_b64 v[80:81], 7, v[80:81]
	v_lshl_or_b32 v80, v132, 2, v80
	v_lshl_add_u64 v[82:83], s[6:7], 0, v[80:81]
	v_lshl_add_u64 v[80:81], s[8:9], 0, v[80:81]
	s_waitcnt vmcnt(12)
	v_mov_b32_e32 v64, v236
	v_mov_b32_e32 v68, v237
	v_pk_mul_f32 v[80:81], v[78:79], v[64:65] op_sel_hi:[1,0]
	v_pk_mul_f32 v[82:83], v[78:79], v[68:69] op_sel:[1,0] op_sel_hi:[0,0]
	v_pk_fma_f32 v[78:79], v[78:79], v[64:65], v[82:83] op_sel_hi:[1,0,1] neg_lo:[0,0,1] neg_hi:[0,0,1]
	s_nop 0
	v_add_f32_e32 v78, v80, v82
.LBB0_1086:
	s_or_b64 exec, exec, s[48:49]
	s_cbranch_vccz .Lq_pf_skip29
	global_load_dword v236, v251, s[56:57] offset:384
	global_load_dword v237, v251, s[72:73] offset:384
.Lq_pf_skip29:
	v_cvt_pk_bf16_f32 v64, v79, s0
	v_mov_b32_e32 v85, v84
	ds_write_b16 v173, v64 offset:32
	v_cvt_pk_bf16_f32 v64, v78, s0
	v_mov_b32_e32 v68, v65
	ds_write_b16 v174, v64 offset:96
	v_pk_mul_f32 v[64:65], v[68:69], v[84:85]
	s_and_saveexec_b64 s[48:49], vcc
	s_cbranch_execz .LBB0_1088
	v_lshlrev_b64 v[68:69], 7, v[72:73]
	v_lshl_or_b32 v68, v132, 2, v68
	v_lshl_add_u64 v[72:73], s[6:7], 0, v[68:69]
	v_lshl_add_u64 v[68:69], s[8:9], 0, v[68:69]
	s_waitcnt vmcnt(12)
	v_mov_b32_e32 v72, v238
	s_nop 0
	v_mov_b32_e32 v68, v239
	v_pk_mul_f32 v[78:79], v[64:65], v[72:73] op_sel_hi:[1,0]
	v_pk_mul_f32 v[68:69], v[64:65], v[68:69] op_sel:[1,0] op_sel_hi:[0,0]
	v_pk_fma_f32 v[64:65], v[64:65], v[72:73], v[68:69] op_sel_hi:[1,0,1] neg_lo:[0,0,1] neg_hi:[0,0,1]
	s_nop 0
	v_add_f32_e32 v64, v78, v68
.LBB0_1088:
	s_or_b64 exec, exec, s[48:49]
	s_cbranch_vccz .Lq_pf_skip30
	global_load_dword v238, v251, s[56:57] offset:64
	global_load_dword v239, v251, s[72:73] offset:64
.Lq_pf_skip30:
	v_cvt_pk_bf16_f32 v65, v65, s0
	v_cvt_pk_bf16_f32 v64, v64, s0
	v_mov_b32_e32 v87, v86
	ds_write_b16 v175, v65 offset:32
	ds_write_b16 v176, v64 offset:96
	v_mov_b32_e32 v64, v66
	v_mov_b32_e32 v65, v70
	v_pk_mul_f32 v[64:65], v[64:65], v[86:87]
	s_and_saveexec_b64 s[48:49], vcc
	s_cbranch_execz .LBB0_1090
	v_lshlrev_b64 v[68:69], 7, v[76:77]
	v_lshl_or_b32 v68, v132, 2, v68
	v_lshl_add_u64 v[72:73], s[6:7], 0, v[68:69]
	v_lshl_add_u64 v[68:69], s[8:9], 0, v[68:69]
	s_waitcnt vmcnt(12)
	v_mov_b32_e32 v66, v240
	s_nop 0
	v_mov_b32_e32 v68, v241
	v_pk_mul_f32 v[72:73], v[64:65], v[66:67] op_sel_hi:[1,0]
	v_pk_mul_f32 v[68:69], v[64:65], v[68:69] op_sel:[1,0] op_sel_hi:[0,0]
	v_pk_fma_f32 v[64:65], v[64:65], v[66:67], v[68:69] op_sel_hi:[1,0,1] neg_lo:[0,0,1] neg_hi:[0,0,1]
	s_nop 0
	v_add_f32_e32 v64, v72, v68
.LBB0_1090:
	s_or_b64 exec, exec, s[48:49]
	s_cbranch_vccz .Lq_pf_skip31
	global_load_dword v240, v251, s[56:57] offset:192
	global_load_dword v241, v251, s[72:73] offset:192
.Lq_pf_skip31:
	v_mov_b32_e32 v89, v88
	v_cvt_pk_bf16_f32 v65, v65, s0
	v_cvt_pk_bf16_f32 v64, v64, s0
	v_mov_b32_e32 v70, v67
	ds_write_b16 v177, v65 offset:32
	ds_write_b16 v178, v64 offset:96
	v_pk_mul_f32 v[64:65], v[70:71], v[88:89]
	s_and_saveexec_b64 s[48:49], vcc
	s_cbranch_execz .LBB0_1092
	v_lshlrev_b64 v[66:67], 7, v[74:75]
	v_lshl_or_b32 v66, v132, 2, v66
	v_lshl_add_u64 v[68:69], s[6:7], 0, v[66:67]
	v_lshl_add_u64 v[66:67], s[8:9], 0, v[66:67]
	s_waitcnt vmcnt(12)
	v_mov_b32_e32 v68, v242
	s_nop 0
	v_mov_b32_e32 v66, v243
	v_pk_mul_f32 v[70:71], v[64:65], v[68:69] op_sel_hi:[1,0]
	v_pk_mul_f32 v[66:67], v[64:65], v[66:67] op_sel:[1,0] op_sel_hi:[0,0]
	v_pk_fma_f32 v[64:65], v[64:65], v[68:69], v[66:67] op_sel_hi:[1,0,1] neg_lo:[0,0,1] neg_hi:[0,0,1]
	s_nop 0
	v_add_f32_e32 v64, v70, v66
.LBB0_1092:
	s_or_b64 exec, exec, s[48:49]
	s_cbranch_vccz .Lq_pf_skip32
	global_load_dword v242, v251, s[56:57] offset:320
	global_load_dword v243, v251, s[72:73] offset:320
.Lq_pf_skip32:
	v_cvt_pk_bf16_f32 v65, v65, s0
	v_cvt_pk_bf16_f32 v64, v64, s0
	ds_write_b16 v179, v65 offset:32
	ds_write_b16 v180, v64 offset:96
	ds_read_b32 v66, v149 offset:256
	v_mov_b32_e32 v68, v56
	v_or_b32_e32 v56, 64, v133
	v_mov_b32_e32 v69, v60
	v_or_b32_e32 v64, v231, v56
	s_waitcnt lgkmcnt(0)
	v_pk_mul_f32 v[70:71], v[68:69], v[66:67] op_sel_hi:[1,0]
	v_ashrrev_i32_e32 v65, 31, v64
	s_and_saveexec_b64 s[48:49], vcc
	s_cbranch_execz .LBB0_1094
	v_lshlrev_b64 v[68:69], 7, v[64:65]
	v_lshl_or_b32 v68, v130, 2, v68
	v_lshl_add_u64 v[72:73], s[6:7], 0, v[68:69]
	v_lshl_add_u64 v[68:69], s[8:9], 0, v[68:69]
	s_waitcnt vmcnt(12)
	v_mov_b32_e32 v56, v244
	v_mov_b32_e32 v60, v245
	v_pk_mul_f32 v[68:69], v[70:71], v[56:57] op_sel_hi:[1,0]
	v_pk_mul_f32 v[72:73], v[70:71], v[60:61] op_sel:[1,0] op_sel_hi:[0,0]
	v_pk_fma_f32 v[70:71], v[70:71], v[56:57], v[72:73] op_sel_hi:[1,0,1] neg_lo:[0,0,1] neg_hi:[0,0,1]
	s_nop 0
	v_add_f32_e32 v70, v68, v72
.LBB0_1094:
	s_or_b64 exec, exec, s[48:49]
	s_cbranch_vccz .Lq_pf_skip33
	global_load_dword v244, v251, s[56:57] offset:448
	global_load_dword v245, v251, s[72:73] offset:448
.Lq_pf_skip33:
	ds_read_b32 v68, v149 offset:260
	v_cvt_pk_bf16_f32 v56, v71, s0
	ds_write_b16 v182, v56
	v_cvt_pk_bf16_f32 v56, v70, s0
	ds_write_b16 v183, v56 offset:64
	v_or_b32_e32 v56, 0x41, v133
	v_mov_b32_e32 v60, v57
	v_or_b32_e32 v56, v231, v56
	s_waitcnt lgkmcnt(2)
	v_pk_mul_f32 v[60:61], v[60:61], v[68:69] op_sel_hi:[1,0]
	v_ashrrev_i32_e32 v57, 31, v56
	s_and_saveexec_b64 s[48:49], vcc
	s_cbranch_execz .LBB0_1096
	v_lshlrev_b64 v[70:71], 7, v[56:57]
	v_lshl_or_b32 v70, v130, 2, v70
	v_lshl_add_u64 v[72:73], s[6:7], 0, v[70:71]
	v_lshl_add_u64 v[70:71], s[8:9], 0, v[70:71]
	s_waitcnt vmcnt(12)
	v_mov_b32_e32 v72, v246
	s_nop 0
	v_mov_b32_e32 v70, v247
	v_pk_mul_f32 v[74:75], v[60:61], v[72:73] op_sel_hi:[1,0]
	v_pk_mul_f32 v[70:71], v[60:61], v[70:71] op_sel:[1,0] op_sel_hi:[0,0]
	v_pk_fma_f32 v[60:61], v[60:61], v[72:73], v[70:71] op_sel_hi:[1,0,1] neg_lo:[0,0,1] neg_hi:[0,0,1]
	s_nop 0
	v_add_f32_e32 v60, v74, v70
.LBB0_1096:
	s_or_b64 exec, exec, s[48:49]
	s_cbranch_vccz .Lq_pf_skip34
	s_add_u32 s56, s56, 0x800
	s_addc_u32 s57, s57, 0
	s_add_u32 s72, s72, 0x800
	s_addc_u32 s73, s73, 0
	global_load_dword v246, v251, s[56:57]
	global_load_dword v247, v251, s[72:73]
.Lq_pf_skip34:
	ds_read_b32 v70, v149 offset:264
	v_cvt_pk_bf16_f32 v61, v61, s0
	v_cvt_pk_bf16_f32 v60, v60, s0
	ds_write_b16 v184, v61
	ds_write_b16 v185, v60 offset:64
	v_mov_b32_e32 v60, v58
	v_mov_b32_e32 v61, v62
	s_waitcnt lgkmcnt(2)
	v_pk_mul_f32 v[74:75], v[60:61], v[70:71] op_sel_hi:[1,0]
	v_or_b32_e32 v60, v231, v186
	v_ashrrev_i32_e32 v61, 31, v60
	s_and_saveexec_b64 s[48:49], vcc
	s_cbranch_execz .LBB0_1098
	v_lshlrev_b64 v[72:73], 7, v[60:61]
	v_lshl_or_b32 v72, v130, 2, v72
	v_lshl_add_u64 v[76:77], s[6:7], 0, v[72:73]
	v_lshl_add_u64 v[72:73], s[8:9], 0, v[72:73]
	s_waitcnt vmcnt(12)
	v_mov_b32_e32 v58, v248
	v_mov_b32_e32 v62, v249
	v_pk_mul_f32 v[72:73], v[74:75], v[58:59] op_sel_hi:[1,0]
	v_pk_mul_f32 v[76:77], v[74:75], v[62:63] op_sel:[1,0] op_sel_hi:[0,0]
	v_pk_fma_f32 v[74:75], v[74:75], v[58:59], v[76:77] op_sel_hi:[1,0,1] neg_lo:[0,0,1] neg_hi:[0,0,1]
	s_nop 0
	v_add_f32_e32 v74, v72, v76
.LBB0_1098:
	s_or_b64 exec, exec, s[48:49]
	s_cbranch_vccz .Lq_pf_skip35
	global_load_dword v248, v251, s[56:57] offset:128
	global_load_dword v249, v251, s[72:73] offset:128
.Lq_pf_skip35:
	ds_read_b32 v72, v149 offset:268
	v_cvt_pk_bf16_f32 v58, v75, s0
	ds_write_b16 v187, v58
	v_cvt_pk_bf16_f32 v58, v74, s0
	ds_write_b16 v188, v58 offset:64
	v_mov_b32_e32 v62, v59
	v_or_b32_e32 v58, v231, v189
	s_waitcnt lgkmcnt(2)
	v_pk_mul_f32 v[62:63], v[62:63], v[72:73] op_sel_hi:[1,0]
	v_ashrrev_i32_e32 v59, 31, v58
	s_and_saveexec_b64 s[48:49], vcc
	s_cbranch_execz .LBB0_1100
	v_lshlrev_b64 v[74:75], 7, v[58:59]
	v_lshl_or_b32 v74, v130, 2, v74
	v_lshl_add_u64 v[76:77], s[6:7], 0, v[74:75]
	v_lshl_add_u64 v[74:75], s[8:9], 0, v[74:75]
	s_waitcnt vmcnt(12)
	v_mov_b32_e32 v76, v236
	s_nop 0
	v_mov_b32_e32 v74, v237
	v_pk_mul_f32 v[78:79], v[62:63], v[76:77] op_sel_hi:[1,0]
	v_pk_mul_f32 v[74:75], v[62:63], v[74:75] op_sel:[1,0] op_sel_hi:[0,0]
	v_pk_fma_f32 v[62:63], v[62:63], v[76:77], v[74:75] op_sel_hi:[1,0,1] neg_lo:[0,0,1] neg_hi:[0,0,1]
	s_nop 0
	v_add_f32_e32 v62, v78, v74
.LBB0_1100:
	s_or_b64 exec, exec, s[48:49]
	s_cbranch_vccz .Lq_pf_skip36
	global_load_dword v236, v251, s[56:57] offset:256
	global_load_dword v237, v251, s[72:73] offset:256
.Lq_pf_skip36:
	v_cvt_pk_bf16_f32 v63, v63, s0
	v_cvt_pk_bf16_f32 v62, v62, s0
	v_mov_b32_e32 v67, v66
	ds_write_b16 v190, v63
	ds_write_b16 v191, v62 offset:64
	v_mov_b32_e32 v62, v48
	v_mov_b32_e32 v63, v52
	v_pk_mul_f32 v[62:63], v[62:63], v[66:67]
	s_and_saveexec_b64 s[48:49], vcc
	s_cbranch_execz .LBB0_1102
	v_lshlrev_b64 v[64:65], 7, v[64:65]
	v_lshl_or_b32 v64, v132, 2, v64
	v_lshl_add_u64 v[66:67], s[6:7], 0, v[64:65]
	v_lshl_add_u64 v[64:65], s[8:9], 0, v[64:65]
	s_waitcnt vmcnt(12)
	v_mov_b32_e32 v48, v238
	v_mov_b32_e32 v52, v239
	v_pk_mul_f32 v[64:65], v[62:63], v[48:49] op_sel_hi:[1,0]
	v_pk_mul_f32 v[66:67], v[62:63], v[52:53] op_sel:[1,0] op_sel_hi:[0,0]
	v_pk_fma_f32 v[62:63], v[62:63], v[48:49], v[66:67] op_sel_hi:[1,0,1] neg_lo:[0,0,1] neg_hi:[0,0,1]
	s_nop 0
	v_add_f32_e32 v62, v64, v66
.LBB0_1102:
	s_or_b64 exec, exec, s[48:49]
	s_cbranch_vccz .Lq_pf_skip37
	global_load_dword v238, v251, s[56:57] offset:384
	global_load_dword v239, v251, s[72:73] offset:384
.Lq_pf_skip37:
	v_cvt_pk_bf16_f32 v48, v63, s0
	v_mov_b32_e32 v69, v68
	ds_write_b16 v182, v48 offset:32
	v_cvt_pk_bf16_f32 v48, v62, s0
	v_mov_b32_e32 v52, v49
	ds_write_b16 v183, v48 offset:96
	v_pk_mul_f32 v[48:49], v[52:53], v[68:69]
	s_and_saveexec_b64 s[48:49], vcc
	s_cbranch_execz .LBB0_1104
	v_lshlrev_b64 v[52:53], 7, v[56:57]
	v_lshl_or_b32 v52, v132, 2, v52
	v_lshl_add_u64 v[56:57], s[6:7], 0, v[52:53]
	v_lshl_add_u64 v[52:53], s[8:9], 0, v[52:53]
	s_waitcnt vmcnt(12)
	v_mov_b32_e32 v56, v240
	s_nop 0
	v_mov_b32_e32 v52, v241
	v_pk_mul_f32 v[62:63], v[48:49], v[56:57] op_sel_hi:[1,0]
	v_pk_mul_f32 v[52:53], v[48:49], v[52:53] op_sel:[1,0] op_sel_hi:[0,0]
	v_pk_fma_f32 v[48:49], v[48:49], v[56:57], v[52:53] op_sel_hi:[1,0,1] neg_lo:[0,0,1] neg_hi:[0,0,1]
	s_nop 0
	v_add_f32_e32 v48, v62, v52
.LBB0_1104:
	s_or_b64 exec, exec, s[48:49]
	s_cbranch_vccz .Lq_pf_skip38
	global_load_dword v240, v251, s[56:57] offset:64
	global_load_dword v241, v251, s[72:73] offset:64
.Lq_pf_skip38:
	v_cvt_pk_bf16_f32 v49, v49, s0
	v_cvt_pk_bf16_f32 v48, v48, s0
	v_mov_b32_e32 v71, v70
	ds_write_b16 v184, v49 offset:32
	ds_write_b16 v185, v48 offset:96
	v_mov_b32_e32 v48, v50
	v_mov_b32_e32 v49, v54
	v_pk_mul_f32 v[48:49], v[48:49], v[70:71]
	s_and_saveexec_b64 s[48:49], vcc
	s_cbranch_execz .LBB0_1106
	v_lshlrev_b64 v[52:53], 7, v[60:61]
	v_lshl_or_b32 v52, v132, 2, v52
	v_lshl_add_u64 v[56:57], s[6:7], 0, v[52:53]
	v_lshl_add_u64 v[52:53], s[8:9], 0, v[52:53]
	s_waitcnt vmcnt(12)
	v_mov_b32_e32 v50, v242
	s_nop 0
	v_mov_b32_e32 v52, v243
	v_pk_mul_f32 v[56:57], v[48:49], v[50:51] op_sel_hi:[1,0]
	v_pk_mul_f32 v[52:53], v[48:49], v[52:53] op_sel:[1,0] op_sel_hi:[0,0]
	v_pk_fma_f32 v[48:49], v[48:49], v[50:51], v[52:53] op_sel_hi:[1,0,1] neg_lo:[0,0,1] neg_hi:[0,0,1]
	s_nop 0
	v_add_f32_e32 v48, v56, v52
.LBB0_1106:
	s_or_b64 exec, exec, s[48:49]
	s_cbranch_vccz .Lq_pf_skip39
	global_load_dword v242, v251, s[56:57] offset:192
	global_load_dword v243, v251, s[72:73] offset:192
.Lq_pf_skip39:
	v_mov_b32_e32 v73, v72
	v_cvt_pk_bf16_f32 v49, v49, s0
	v_cvt_pk_bf16_f32 v48, v48, s0
	v_mov_b32_e32 v54, v51
	ds_write_b16 v187, v49 offset:32
	ds_write_b16 v188, v48 offset:96
	v_pk_mul_f32 v[48:49], v[54:55], v[72:73]
	s_and_saveexec_b64 s[48:49], vcc
	s_cbranch_execz .LBB0_1108
	v_lshlrev_b64 v[50:51], 7, v[58:59]
	v_lshl_or_b32 v50, v132, 2, v50
	v_lshl_add_u64 v[52:53], s[6:7], 0, v[50:51]
	v_lshl_add_u64 v[50:51], s[8:9], 0, v[50:51]
	s_waitcnt vmcnt(12)
	v_mov_b32_e32 v52, v244
	s_nop 0
	v_mov_b32_e32 v50, v245
	v_pk_mul_f32 v[54:55], v[48:49], v[52:53] op_sel_hi:[1,0]
	v_pk_mul_f32 v[50:51], v[48:49], v[50:51] op_sel:[1,0] op_sel_hi:[0,0]
	v_pk_fma_f32 v[48:49], v[48:49], v[52:53], v[50:51] op_sel_hi:[1,0,1] neg_lo:[0,0,1] neg_hi:[0,0,1]
	s_nop 0
	v_add_f32_e32 v48, v54, v50
.LBB0_1108:
	s_or_b64 exec, exec, s[48:49]
	s_cbranch_vccz .Lq_pf_skip40
	global_load_dword v244, v251, s[56:57] offset:320
	global_load_dword v245, v251, s[72:73] offset:320
.Lq_pf_skip40:
	v_cvt_pk_bf16_f32 v49, v49, s0
	v_cvt_pk_bf16_f32 v48, v48, s0
	ds_write_b16 v190, v49 offset:32
	ds_write_b16 v191, v48 offset:96
	ds_read_b32 v50, v149 offset:320
	v_mov_b32_e32 v52, v40
	v_mov_b32_e32 v53, v44
	v_or_b32_e32 v48, v231, v192
	v_ashrrev_i32_e32 v49, 31, v48
	s_waitcnt lgkmcnt(0)
	v_pk_mul_f32 v[54:55], v[52:53], v[50:51] op_sel_hi:[1,0]
	s_and_saveexec_b64 s[48:49], vcc
	s_cbranch_execz .LBB0_1110
	v_lshlrev_b64 v[52:53], 7, v[48:49]
	v_lshl_or_b32 v52, v130, 2, v52
	v_lshl_add_u64 v[56:57], s[6:7], 0, v[52:53]
	v_lshl_add_u64 v[52:53], s[8:9], 0, v[52:53]
	s_waitcnt vmcnt(12)
	v_mov_b32_e32 v40, v246
	v_mov_b32_e32 v44, v247
	v_pk_mul_f32 v[52:53], v[54:55], v[40:41] op_sel_hi:[1,0]
	v_pk_mul_f32 v[56:57], v[54:55], v[44:45] op_sel:[1,0] op_sel_hi:[0,0]
	v_pk_fma_f32 v[54:55], v[54:55], v[40:41], v[56:57] op_sel_hi:[1,0,1] neg_lo:[0,0,1] neg_hi:[0,0,1]
	s_nop 0
	v_add_f32_e32 v54, v52, v56
.LBB0_1110:
	s_or_b64 exec, exec, s[48:49]
	s_cbranch_vccz .Lq_pf_skip41
	global_load_dword v246, v251, s[56:57] offset:448
	global_load_dword v247, v251, s[72:73] offset:448
.Lq_pf_skip41:
	ds_read_b32 v52, v149 offset:324
	v_cvt_pk_bf16_f32 v40, v55, s0
	ds_write_b16 v193, v40
	v_cvt_pk_bf16_f32 v40, v54, s0
	ds_write_b16 v194, v40 offset:64
	v_mov_b32_e32 v44, v41
	v_or_b32_e32 v40, v231, v195
	s_waitcnt lgkmcnt(2)
	v_pk_mul_f32 v[44:45], v[44:45], v[52:53] op_sel_hi:[1,0]
	v_ashrrev_i32_e32 v41, 31, v40
	s_and_saveexec_b64 s[48:49], vcc
	s_cbranch_execz .LBB0_1112
	v_lshlrev_b64 v[54:55], 7, v[40:41]
	v_lshl_or_b32 v54, v130, 2, v54
	v_lshl_add_u64 v[56:57], s[6:7], 0, v[54:55]
	v_lshl_add_u64 v[54:55], s[8:9], 0, v[54:55]
	s_waitcnt vmcnt(12)
	v_mov_b32_e32 v56, v248
	s_nop 0
	v_mov_b32_e32 v54, v249
	v_pk_mul_f32 v[58:59], v[44:45], v[56:57] op_sel_hi:[1,0]
	v_pk_mul_f32 v[54:55], v[44:45], v[54:55] op_sel:[1,0] op_sel_hi:[0,0]
	v_pk_fma_f32 v[44:45], v[44:45], v[56:57], v[54:55] op_sel_hi:[1,0,1] neg_lo:[0,0,1] neg_hi:[0,0,1]
	s_nop 0
	v_add_f32_e32 v44, v58, v54
.LBB0_1112:
	s_or_b64 exec, exec, s[48:49]
	s_cbranch_vccz .Lq_pf_skip42
	s_add_u32 s56, s56, 0x800
	s_addc_u32 s57, s57, 0
	s_add_u32 s72, s72, 0x800
	s_addc_u32 s73, s73, 0
	global_load_dword v248, v251, s[56:57]
	global_load_dword v249, v251, s[72:73]
.Lq_pf_skip42:
	ds_read_b32 v54, v149 offset:328
	v_cvt_pk_bf16_f32 v45, v45, s0
	v_cvt_pk_bf16_f32 v44, v44, s0
	ds_write_b16 v196, v45
	ds_write_b16 v197, v44 offset:64
	v_mov_b32_e32 v44, v42
	v_mov_b32_e32 v45, v46
	s_waitcnt lgkmcnt(2)
	v_pk_mul_f32 v[58:59], v[44:45], v[54:55] op_sel_hi:[1,0]
	v_or_b32_e32 v44, v231, v198
	v_ashrrev_i32_e32 v45, 31, v44
	s_and_saveexec_b64 s[48:49], vcc
	s_cbranch_execz .LBB0_1114
	v_lshlrev_b64 v[56:57], 7, v[44:45]
	v_lshl_or_b32 v56, v130, 2, v56
	v_lshl_add_u64 v[60:61], s[6:7], 0, v[56:57]
	v_lshl_add_u64 v[56:57], s[8:9], 0, v[56:57]
	s_waitcnt vmcnt(12)
	v_mov_b32_e32 v42, v236
	v_mov_b32_e32 v46, v237
	v_pk_mul_f32 v[56:57], v[58:59], v[42:43] op_sel_hi:[1,0]
	v_pk_mul_f32 v[60:61], v[58:59], v[46:47] op_sel:[1,0] op_sel_hi:[0,0]
	v_pk_fma_f32 v[58:59], v[58:59], v[42:43], v[60:61] op_sel_hi:[1,0,1] neg_lo:[0,0,1] neg_hi:[0,0,1]
	s_nop 0
	v_add_f32_e32 v58, v56, v60
.LBB0_1114:
	s_or_b64 exec, exec, s[48:49]
	s_cbranch_vccz .Lq_pf_skip43
	global_load_dword v236, v251, s[56:57] offset:128
	global_load_dword v237, v251, s[72:73] offset:128
.Lq_pf_skip43:
	ds_read_b32 v56, v149 offset:332
	v_cvt_pk_bf16_f32 v42, v59, s0
	ds_write_b16 v199, v42
	v_cvt_pk_bf16_f32 v42, v58, s0
	ds_write_b16 v200, v42 offset:64
	v_mov_b32_e32 v46, v43
	v_or_b32_e32 v42, v231, v201
	s_waitcnt lgkmcnt(2)
	v_pk_mul_f32 v[46:47], v[46:47], v[56:57] op_sel_hi:[1,0]
	v_ashrrev_i32_e32 v43, 31, v42
	s_and_saveexec_b64 s[48:49], vcc
	s_cbranch_execz .LBB0_1116
	v_lshlrev_b64 v[58:59], 7, v[42:43]
	v_lshl_or_b32 v58, v130, 2, v58
	v_lshl_add_u64 v[60:61], s[6:7], 0, v[58:59]
	v_lshl_add_u64 v[58:59], s[8:9], 0, v[58:59]
	s_waitcnt vmcnt(12)
	v_mov_b32_e32 v60, v238
	s_nop 0
	v_mov_b32_e32 v58, v239
	v_pk_mul_f32 v[62:63], v[46:47], v[60:61] op_sel_hi:[1,0]
	v_pk_mul_f32 v[58:59], v[46:47], v[58:59] op_sel:[1,0] op_sel_hi:[0,0]
	v_pk_fma_f32 v[46:47], v[46:47], v[60:61], v[58:59] op_sel_hi:[1,0,1] neg_lo:[0,0,1] neg_hi:[0,0,1]
	s_nop 0
	v_add_f32_e32 v46, v62, v58
.LBB0_1116:
	s_or_b64 exec, exec, s[48:49]
	s_cbranch_vccz .Lq_pf_skip44
	global_load_dword v238, v251, s[56:57] offset:256
	global_load_dword v239, v251, s[72:73] offset:256
.Lq_pf_skip44:
	v_cvt_pk_bf16_f32 v47, v47, s0
	v_cvt_pk_bf16_f32 v46, v46, s0
	v_mov_b32_e32 v51, v50
	ds_write_b16 v202, v47
	ds_write_b16 v203, v46 offset:64
	v_mov_b32_e32 v46, v32
	v_mov_b32_e32 v47, v36
	v_pk_mul_f32 v[46:47], v[46:47], v[50:51]
	s_and_saveexec_b64 s[48:49], vcc
	s_cbranch_execz .LBB0_1118
	v_lshlrev_b64 v[48:49], 7, v[48:49]
	v_lshl_or_b32 v48, v132, 2, v48
	v_lshl_add_u64 v[50:51], s[6:7], 0, v[48:49]
	v_lshl_add_u64 v[48:49], s[8:9], 0, v[48:49]
	s_waitcnt vmcnt(12)
	v_mov_b32_e32 v32, v240
	v_mov_b32_e32 v36, v241
	v_pk_mul_f32 v[48:49], v[46:47], v[32:33] op_sel_hi:[1,0]
	v_pk_mul_f32 v[50:51], v[46:47], v[36:37] op_sel:[1,0] op_sel_hi:[0,0]
	v_pk_fma_f32 v[46:47], v[46:47], v[32:33], v[50:51] op_sel_hi:[1,0,1] neg_lo:[0,0,1] neg_hi:[0,0,1]
	s_nop 0
	v_add_f32_e32 v46, v48, v50
.LBB0_1118:
	s_or_b64 exec, exec, s[48:49]
	s_cbranch_vccz .Lq_pf_skip45
	global_load_dword v240, v251, s[56:57] offset:384
	global_load_dword v241, v251, s[72:73] offset:384
.Lq_pf_skip45:
	v_cvt_pk_bf16_f32 v32, v47, s0
	v_mov_b32_e32 v53, v52
	ds_write_b16 v193, v32 offset:32
	v_cvt_pk_bf16_f32 v32, v46, s0
	v_mov_b32_e32 v36, v33
	ds_write_b16 v194, v32 offset:96
	v_pk_mul_f32 v[32:33], v[36:37], v[52:53]
	s_and_saveexec_b64 s[48:49], vcc
	s_cbranch_execz .LBB0_1120
	v_lshlrev_b64 v[36:37], 7, v[40:41]
	v_lshl_or_b32 v36, v132, 2, v36
	v_lshl_add_u64 v[40:41], s[6:7], 0, v[36:37]
	v_lshl_add_u64 v[36:37], s[8:9], 0, v[36:37]
	s_waitcnt vmcnt(12)
	v_mov_b32_e32 v40, v242
	s_nop 0
	v_mov_b32_e32 v36, v243
	v_pk_mul_f32 v[46:47], v[32:33], v[40:41] op_sel_hi:[1,0]
	v_pk_mul_f32 v[36:37], v[32:33], v[36:37] op_sel:[1,0] op_sel_hi:[0,0]
	v_pk_fma_f32 v[32:33], v[32:33], v[40:41], v[36:37] op_sel_hi:[1,0,1] neg_lo:[0,0,1] neg_hi:[0,0,1]
	s_nop 0
	v_add_f32_e32 v32, v46, v36
.LBB0_1120:
	s_or_b64 exec, exec, s[48:49]
	s_cbranch_vccz .Lq_pf_skip46
	global_load_dword v242, v251, s[56:57] offset:64
	global_load_dword v243, v251, s[72:73] offset:64
.Lq_pf_skip46:
	v_cvt_pk_bf16_f32 v33, v33, s0
	v_cvt_pk_bf16_f32 v32, v32, s0
	v_mov_b32_e32 v55, v54
	ds_write_b16 v196, v33 offset:32
	ds_write_b16 v197, v32 offset:96
	v_mov_b32_e32 v32, v34
	v_mov_b32_e32 v33, v38
	v_pk_mul_f32 v[32:33], v[32:33], v[54:55]
	s_and_saveexec_b64 s[48:49], vcc
	s_cbranch_execz .LBB0_1122
	v_lshlrev_b64 v[36:37], 7, v[44:45]
	v_lshl_or_b32 v36, v132, 2, v36
	v_lshl_add_u64 v[40:41], s[6:7], 0, v[36:37]
	v_lshl_add_u64 v[36:37], s[8:9], 0, v[36:37]
	s_waitcnt vmcnt(12)
	v_mov_b32_e32 v34, v244
	s_nop 0
	v_mov_b32_e32 v36, v245
	v_pk_mul_f32 v[40:41], v[32:33], v[34:35] op_sel_hi:[1,0]
	v_pk_mul_f32 v[36:37], v[32:33], v[36:37] op_sel:[1,0] op_sel_hi:[0,0]
	v_pk_fma_f32 v[32:33], v[32:33], v[34:35], v[36:37] op_sel_hi:[1,0,1] neg_lo:[0,0,1] neg_hi:[0,0,1]
	s_nop 0
	v_add_f32_e32 v32, v40, v36
.LBB0_1122:
	s_or_b64 exec, exec, s[48:49]
	s_cbranch_vccz .Lq_pf_skip47
	global_load_dword v244, v251, s[56:57] offset:192
	global_load_dword v245, v251, s[72:73] offset:192
.Lq_pf_skip47:
	v_mov_b32_e32 v57, v56
	v_cvt_pk_bf16_f32 v33, v33, s0
	v_cvt_pk_bf16_f32 v32, v32, s0
	v_mov_b32_e32 v38, v35
	ds_write_b16 v199, v33 offset:32
	ds_write_b16 v200, v32 offset:96
	v_pk_mul_f32 v[32:33], v[38:39], v[56:57]
	s_and_saveexec_b64 s[48:49], vcc
	s_cbranch_execz .LBB0_1124
	v_lshlrev_b64 v[34:35], 7, v[42:43]
	v_lshl_or_b32 v34, v132, 2, v34
	v_lshl_add_u64 v[36:37], s[6:7], 0, v[34:35]
	v_lshl_add_u64 v[34:35], s[8:9], 0, v[34:35]
	s_waitcnt vmcnt(12)
	v_mov_b32_e32 v36, v246
	s_nop 0
	v_mov_b32_e32 v34, v247
	v_pk_mul_f32 v[38:39], v[32:33], v[36:37] op_sel_hi:[1,0]
	v_pk_mul_f32 v[34:35], v[32:33], v[34:35] op_sel:[1,0] op_sel_hi:[0,0]
	v_pk_fma_f32 v[32:33], v[32:33], v[36:37], v[34:35] op_sel_hi:[1,0,1] neg_lo:[0,0,1] neg_hi:[0,0,1]
	s_nop 0
	v_add_f32_e32 v32, v38, v34
.LBB0_1124:
	s_or_b64 exec, exec, s[48:49]
	s_cbranch_vccz .Lq_pf_skip48
	global_load_dword v246, v251, s[56:57] offset:320
	global_load_dword v247, v251, s[72:73] offset:320
.Lq_pf_skip48:
	v_cvt_pk_bf16_f32 v33, v33, s0
	v_cvt_pk_bf16_f32 v32, v32, s0
	ds_write_b16 v202, v33 offset:32
	ds_write_b16 v203, v32 offset:96
	ds_read_b32 v34, v149 offset:384
	v_mov_b32_e32 v36, v24
	v_mov_b32_e32 v37, v28
	v_or_b32_e32 v32, v231, v204
	v_ashrrev_i32_e32 v33, 31, v32
	s_waitcnt lgkmcnt(0)
	v_pk_mul_f32 v[38:39], v[36:37], v[34:35] op_sel_hi:[1,0]
	s_and_saveexec_b64 s[48:49], vcc
	s_cbranch_execz .LBB0_1126
	v_lshlrev_b64 v[36:37], 7, v[32:33]
	v_lshl_or_b32 v36, v130, 2, v36
	v_lshl_add_u64 v[40:41], s[6:7], 0, v[36:37]
	v_lshl_add_u64 v[36:37], s[8:9], 0, v[36:37]
	s_waitcnt vmcnt(12)
	v_mov_b32_e32 v24, v248
	v_mov_b32_e32 v28, v249
	v_pk_mul_f32 v[36:37], v[38:39], v[24:25] op_sel_hi:[1,0]
	v_pk_mul_f32 v[40:41], v[38:39], v[28:29] op_sel:[1,0] op_sel_hi:[0,0]
	v_pk_fma_f32 v[38:39], v[38:39], v[24:25], v[40:41] op_sel_hi:[1,0,1] neg_lo:[0,0,1] neg_hi:[0,0,1]
	s_nop 0
	v_add_f32_e32 v38, v36, v40
.LBB0_1126:
	s_or_b64 exec, exec, s[48:49]
	s_cbranch_vccz .Lq_pf_skip49
	global_load_dword v248, v251, s[56:57] offset:448
	global_load_dword v249, v251, s[72:73] offset:448
.Lq_pf_skip49:
	ds_read_b32 v36, v149 offset:388
	v_cvt_pk_bf16_f32 v24, v39, s0
	ds_write_b16 v205, v24
	v_cvt_pk_bf16_f32 v24, v38, s0
	ds_write_b16 v206, v24 offset:64
	v_mov_b32_e32 v28, v25
	v_or_b32_e32 v24, v231, v207
	s_waitcnt lgkmcnt(2)
	v_pk_mul_f32 v[28:29], v[28:29], v[36:37] op_sel_hi:[1,0]
	v_ashrrev_i32_e32 v25, 31, v24
	s_and_saveexec_b64 s[48:49], vcc
	s_cbranch_execz .LBB0_1128
	v_lshlrev_b64 v[38:39], 7, v[24:25]
	v_lshl_or_b32 v38, v130, 2, v38
	v_lshl_add_u64 v[40:41], s[6:7], 0, v[38:39]
	v_lshl_add_u64 v[38:39], s[8:9], 0, v[38:39]
	s_waitcnt vmcnt(12)
	v_mov_b32_e32 v40, v236
	s_nop 0
	v_mov_b32_e32 v38, v237
	v_pk_mul_f32 v[42:43], v[28:29], v[40:41] op_sel_hi:[1,0]
	v_pk_mul_f32 v[38:39], v[28:29], v[38:39] op_sel:[1,0] op_sel_hi:[0,0]
	v_pk_fma_f32 v[28:29], v[28:29], v[40:41], v[38:39] op_sel_hi:[1,0,1] neg_lo:[0,0,1] neg_hi:[0,0,1]
	s_nop 0
	v_add_f32_e32 v28, v42, v38
.LBB0_1128:
	s_or_b64 exec, exec, s[48:49]
	s_cbranch_vccz .Lq_pf_skip50
	s_add_u32 s56, s56, 0x800
	s_addc_u32 s57, s57, 0
	s_add_u32 s72, s72, 0x800
	s_addc_u32 s73, s73, 0
	global_load_dword v236, v251, s[56:57]
	global_load_dword v237, v251, s[72:73]
.Lq_pf_skip50:
	ds_read_b32 v38, v149 offset:392
	v_cvt_pk_bf16_f32 v29, v29, s0
	v_cvt_pk_bf16_f32 v28, v28, s0
	ds_write_b16 v208, v29
	ds_write_b16 v209, v28 offset:64
	v_mov_b32_e32 v28, v26
	v_mov_b32_e32 v29, v30
	s_waitcnt lgkmcnt(2)
	v_pk_mul_f32 v[42:43], v[28:29], v[38:39] op_sel_hi:[1,0]
	v_or_b32_e32 v28, v231, v210
	v_ashrrev_i32_e32 v29, 31, v28
	s_and_saveexec_b64 s[48:49], vcc
	s_cbranch_execz .LBB0_1130
	v_lshlrev_b64 v[40:41], 7, v[28:29]
	v_lshl_or_b32 v40, v130, 2, v40
	v_lshl_add_u64 v[44:45], s[6:7], 0, v[40:41]
	v_lshl_add_u64 v[40:41], s[8:9], 0, v[40:41]
	s_waitcnt vmcnt(12)
	v_mov_b32_e32 v26, v238
	v_mov_b32_e32 v30, v239
	v_pk_mul_f32 v[40:41], v[42:43], v[26:27] op_sel_hi:[1,0]
	v_pk_mul_f32 v[44:45], v[42:43], v[30:31] op_sel:[1,0] op_sel_hi:[0,0]
	v_pk_fma_f32 v[42:43], v[42:43], v[26:27], v[44:45] op_sel_hi:[1,0,1] neg_lo:[0,0,1] neg_hi:[0,0,1]
	s_nop 0
	v_add_f32_e32 v42, v40, v44
.LBB0_1130:
	s_or_b64 exec, exec, s[48:49]
	s_cbranch_vccz .Lq_pf_skip51
	global_load_dword v238, v251, s[56:57] offset:128
	global_load_dword v239, v251, s[72:73] offset:128
.Lq_pf_skip51:
	ds_read_b32 v40, v149 offset:396
	v_cvt_pk_bf16_f32 v26, v43, s0
	ds_write_b16 v211, v26
	v_cvt_pk_bf16_f32 v26, v42, s0
	ds_write_b16 v212, v26 offset:64
	v_mov_b32_e32 v30, v27
	v_or_b32_e32 v26, v231, v213
	s_waitcnt lgkmcnt(2)
	v_pk_mul_f32 v[30:31], v[30:31], v[40:41] op_sel_hi:[1,0]
	v_ashrrev_i32_e32 v27, 31, v26
	s_and_saveexec_b64 s[48:49], vcc
	s_cbranch_execz .LBB0_1132
	v_lshlrev_b64 v[42:43], 7, v[26:27]
	v_lshl_or_b32 v42, v130, 2, v42
	v_lshl_add_u64 v[44:45], s[6:7], 0, v[42:43]
	v_lshl_add_u64 v[42:43], s[8:9], 0, v[42:43]
	s_waitcnt vmcnt(12)
	v_mov_b32_e32 v44, v240
	s_nop 0
	v_mov_b32_e32 v42, v241
	v_pk_mul_f32 v[46:47], v[30:31], v[44:45] op_sel_hi:[1,0]
	v_pk_mul_f32 v[42:43], v[30:31], v[42:43] op_sel:[1,0] op_sel_hi:[0,0]
	v_pk_fma_f32 v[30:31], v[30:31], v[44:45], v[42:43] op_sel_hi:[1,0,1] neg_lo:[0,0,1] neg_hi:[0,0,1]
	s_nop 0
	v_add_f32_e32 v30, v46, v42
.LBB0_1132:
	s_or_b64 exec, exec, s[48:49]
	s_cbranch_vccz .Lq_pf_skip52
	global_load_dword v240, v251, s[56:57] offset:256
	global_load_dword v241, v251, s[72:73] offset:256
.Lq_pf_skip52:
	v_cvt_pk_bf16_f32 v31, v31, s0
	v_cvt_pk_bf16_f32 v30, v30, s0
	v_mov_b32_e32 v35, v34
	ds_write_b16 v214, v31
	ds_write_b16 v215, v30 offset:64
	v_mov_b32_e32 v30, v16
	v_mov_b32_e32 v31, v20
	v_pk_mul_f32 v[30:31], v[30:31], v[34:35]
	s_and_saveexec_b64 s[48:49], vcc
	s_cbranch_execz .LBB0_1134
	v_lshlrev_b64 v[32:33], 7, v[32:33]
	v_lshl_or_b32 v32, v132, 2, v32
	v_lshl_add_u64 v[34:35], s[6:7], 0, v[32:33]
	v_lshl_add_u64 v[32:33], s[8:9], 0, v[32:33]
	s_waitcnt vmcnt(12)
	v_mov_b32_e32 v16, v242
	v_mov_b32_e32 v20, v243
	v_pk_mul_f32 v[32:33], v[30:31], v[16:17] op_sel_hi:[1,0]
	v_pk_mul_f32 v[34:35], v[30:31], v[20:21] op_sel:[1,0] op_sel_hi:[0,0]
	v_pk_fma_f32 v[30:31], v[30:31], v[16:17], v[34:35] op_sel_hi:[1,0,1] neg_lo:[0,0,1] neg_hi:[0,0,1]
	s_nop 0
	v_add_f32_e32 v30, v32, v34
.LBB0_1134:
	s_or_b64 exec, exec, s[48:49]
	s_cbranch_vccz .Lq_pf_skip53
	global_load_dword v242, v251, s[56:57] offset:384
	global_load_dword v243, v251, s[72:73] offset:384
.Lq_pf_skip53:
	v_cvt_pk_bf16_f32 v16, v31, s0
	v_mov_b32_e32 v37, v36
	ds_write_b16 v205, v16 offset:32
	v_cvt_pk_bf16_f32 v16, v30, s0
	v_mov_b32_e32 v20, v17
	ds_write_b16 v206, v16 offset:96
	v_pk_mul_f32 v[16:17], v[20:21], v[36:37]
	s_and_saveexec_b64 s[48:49], vcc
	s_cbranch_execz .LBB0_1136
	v_lshlrev_b64 v[20:21], 7, v[24:25]
	v_lshl_or_b32 v20, v132, 2, v20
	v_lshl_add_u64 v[24:25], s[6:7], 0, v[20:21]
	v_lshl_add_u64 v[20:21], s[8:9], 0, v[20:21]
	s_waitcnt vmcnt(12)
	v_mov_b32_e32 v24, v244
	s_nop 0
	v_mov_b32_e32 v20, v245
	v_pk_mul_f32 v[30:31], v[16:17], v[24:25] op_sel_hi:[1,0]
	v_pk_mul_f32 v[20:21], v[16:17], v[20:21] op_sel:[1,0] op_sel_hi:[0,0]
	v_pk_fma_f32 v[16:17], v[16:17], v[24:25], v[20:21] op_sel_hi:[1,0,1] neg_lo:[0,0,1] neg_hi:[0,0,1]
	s_nop 0
	v_add_f32_e32 v16, v30, v20
.LBB0_1136:
	s_or_b64 exec, exec, s[48:49]
	s_cbranch_vccz .Lq_pf_skip54
	global_load_dword v244, v251, s[56:57] offset:64
	global_load_dword v245, v251, s[72:73] offset:64
.Lq_pf_skip54:
	v_cvt_pk_bf16_f32 v17, v17, s0
	v_cvt_pk_bf16_f32 v16, v16, s0
	v_mov_b32_e32 v39, v38
	ds_write_b16 v208, v17 offset:32
	ds_write_b16 v209, v16 offset:96
	v_mov_b32_e32 v16, v18
	v_mov_b32_e32 v17, v22
	v_pk_mul_f32 v[16:17], v[16:17], v[38:39]
	s_and_saveexec_b64 s[48:49], vcc
	s_cbranch_execz .LBB0_1138
	v_lshlrev_b64 v[20:21], 7, v[28:29]
	v_lshl_or_b32 v20, v132, 2, v20
	v_lshl_add_u64 v[24:25], s[6:7], 0, v[20:21]
	v_lshl_add_u64 v[20:21], s[8:9], 0, v[20:21]
	s_waitcnt vmcnt(12)
	v_mov_b32_e32 v18, v246
	s_nop 0
	v_mov_b32_e32 v20, v247
	v_pk_mul_f32 v[24:25], v[16:17], v[18:19] op_sel_hi:[1,0]
	v_pk_mul_f32 v[20:21], v[16:17], v[20:21] op_sel:[1,0] op_sel_hi:[0,0]
	v_pk_fma_f32 v[16:17], v[16:17], v[18:19], v[20:21] op_sel_hi:[1,0,1] neg_lo:[0,0,1] neg_hi:[0,0,1]
	s_nop 0
	v_add_f32_e32 v16, v24, v20
.LBB0_1138:
	s_or_b64 exec, exec, s[48:49]
	s_cbranch_vccz .Lq_pf_skip55
	global_load_dword v246, v251, s[56:57] offset:192
	global_load_dword v247, v251, s[72:73] offset:192
.Lq_pf_skip55:
	v_mov_b32_e32 v41, v40
	v_cvt_pk_bf16_f32 v17, v17, s0
	v_cvt_pk_bf16_f32 v16, v16, s0
	v_mov_b32_e32 v22, v19
	ds_write_b16 v211, v17 offset:32
	ds_write_b16 v212, v16 offset:96
	v_pk_mul_f32 v[16:17], v[22:23], v[40:41]
	s_and_saveexec_b64 s[48:49], vcc
	s_cbranch_execz .LBB0_1140
	v_lshlrev_b64 v[18:19], 7, v[26:27]
	v_lshl_or_b32 v18, v132, 2, v18
	v_lshl_add_u64 v[20:21], s[6:7], 0, v[18:19]
	v_lshl_add_u64 v[18:19], s[8:9], 0, v[18:19]
	s_waitcnt vmcnt(12)
	v_mov_b32_e32 v20, v248
	s_nop 0
	v_mov_b32_e32 v18, v249
	v_pk_mul_f32 v[22:23], v[16:17], v[20:21] op_sel_hi:[1,0]
	v_pk_mul_f32 v[18:19], v[16:17], v[18:19] op_sel:[1,0] op_sel_hi:[0,0]
	v_pk_fma_f32 v[16:17], v[16:17], v[20:21], v[18:19] op_sel_hi:[1,0,1] neg_lo:[0,0,1] neg_hi:[0,0,1]
	s_nop 0
	v_add_f32_e32 v16, v22, v18
.LBB0_1140:
	s_or_b64 exec, exec, s[48:49]
	s_cbranch_vccz .Lq_pf_skip56
	global_load_dword v248, v251, s[56:57] offset:320
	global_load_dword v249, v251, s[72:73] offset:320
.Lq_pf_skip56:
	v_cvt_pk_bf16_f32 v17, v17, s0
	v_cvt_pk_bf16_f32 v16, v16, s0
	ds_write_b16 v214, v17 offset:32
	ds_write_b16 v215, v16 offset:96
	ds_read_b32 v18, v149 offset:448
	v_mov_b32_e32 v20, v8
	v_mov_b32_e32 v21, v12
	v_or_b32_e32 v16, v231, v216
	v_ashrrev_i32_e32 v17, 31, v16
	s_waitcnt lgkmcnt(0)
	v_pk_mul_f32 v[22:23], v[20:21], v[18:19] op_sel_hi:[1,0]
	s_and_saveexec_b64 s[48:49], vcc
	s_cbranch_execz .LBB0_1142
	v_lshlrev_b64 v[20:21], 7, v[16:17]
	v_lshl_or_b32 v20, v130, 2, v20
	v_lshl_add_u64 v[24:25], s[6:7], 0, v[20:21]
	v_lshl_add_u64 v[20:21], s[8:9], 0, v[20:21]
	s_waitcnt vmcnt(12)
	v_mov_b32_e32 v8, v236
	v_mov_b32_e32 v12, v237
	v_pk_mul_f32 v[20:21], v[22:23], v[8:9] op_sel_hi:[1,0]
	v_pk_mul_f32 v[24:25], v[22:23], v[12:13] op_sel:[1,0] op_sel_hi:[0,0]
	v_pk_fma_f32 v[22:23], v[22:23], v[8:9], v[24:25] op_sel_hi:[1,0,1] neg_lo:[0,0,1] neg_hi:[0,0,1]
	s_nop 0
	v_add_f32_e32 v22, v20, v24

.Lq_pf_skip57:
	ds_read_b32 v20, v149 offset:452
	v_cvt_pk_bf16_f32 v8, v23, s0
	ds_write_b16 v217, v8
	v_cvt_pk_bf16_f32 v8, v22, s0
	ds_write_b16 v218, v8 offset:64
	v_mov_b32_e32 v12, v9
	v_or_b32_e32 v8, v231, v219
	s_waitcnt lgkmcnt(2)
	v_pk_mul_f32 v[12:13], v[12:13], v[20:21] op_sel_hi:[1,0]
	v_ashrrev_i32_e32 v9, 31, v8
	s_and_saveexec_b64 s[48:49], vcc
	s_cbranch_execz .LBB0_1144
	v_lshlrev_b64 v[22:23], 7, v[8:9]
	v_lshl_or_b32 v22, v130, 2, v22
	v_lshl_add_u64 v[24:25], s[6:7], 0, v[22:23]
	v_lshl_add_u64 v[22:23], s[8:9], 0, v[22:23]
	s_waitcnt vmcnt(12)
	v_mov_b32_e32 v24, v238
	s_nop 0
	v_mov_b32_e32 v22, v239
	v_pk_mul_f32 v[26:27], v[12:13], v[24:25] op_sel_hi:[1,0]
	v_pk_mul_f32 v[22:23], v[12:13], v[22:23] op_sel:[1,0] op_sel_hi:[0,0]
	v_pk_fma_f32 v[12:13], v[12:13], v[24:25], v[22:23] op_sel_hi:[1,0,1] neg_lo:[0,0,1] neg_hi:[0,0,1]
	s_nop 0
	v_add_f32_e32 v12, v26, v22
.LBB0_1144:
	s_or_b64 exec, exec, s[48:49]
	ds_read_b32 v22, v149 offset:456
	v_cvt_pk_bf16_f32 v13, v13, s0
	v_cvt_pk_bf16_f32 v12, v12, s0
	ds_write_b16 v220, v13
	ds_write_b16 v221, v12 offset:64
	v_mov_b32_e32 v12, v10
	v_mov_b32_e32 v13, v14
	s_waitcnt lgkmcnt(2)
	v_pk_mul_f32 v[26:27], v[12:13], v[22:23] op_sel_hi:[1,0]
	v_or_b32_e32 v12, v231, v222
	v_ashrrev_i32_e32 v13, 31, v12
	s_and_saveexec_b64 s[48:49], vcc
	s_cbranch_execz .LBB0_1146
	v_lshlrev_b64 v[24:25], 7, v[12:13]
	v_lshl_or_b32 v24, v130, 2, v24
	v_lshl_add_u64 v[28:29], s[6:7], 0, v[24:25]
	v_lshl_add_u64 v[24:25], s[8:9], 0, v[24:25]
	s_waitcnt vmcnt(10)
	v_mov_b32_e32 v10, v240
	v_mov_b32_e32 v14, v241
	v_pk_mul_f32 v[24:25], v[26:27], v[10:11] op_sel_hi:[1,0]
	v_pk_mul_f32 v[28:29], v[26:27], v[14:15] op_sel:[1,0] op_sel_hi:[0,0]
	v_pk_fma_f32 v[26:27], v[26:27], v[10:11], v[28:29] op_sel_hi:[1,0,1] neg_lo:[0,0,1] neg_hi:[0,0,1]
	s_nop 0
	v_add_f32_e32 v26, v24, v28
.LBB0_1146:
	s_or_b64 exec, exec, s[48:49]
	ds_read_b32 v24, v149 offset:460
	v_cvt_pk_bf16_f32 v10, v27, s0
	ds_write_b16 v223, v10
	v_cvt_pk_bf16_f32 v10, v26, s0
	ds_write_b16 v224, v10 offset:64
	v_mov_b32_e32 v14, v11
	v_or_b32_e32 v10, v231, v225
	s_waitcnt lgkmcnt(2)
	v_pk_mul_f32 v[14:15], v[14:15], v[24:25] op_sel_hi:[1,0]
	v_ashrrev_i32_e32 v11, 31, v10
	s_and_saveexec_b64 s[48:49], vcc
	s_cbranch_execz .LBB0_1148
	v_lshlrev_b64 v[26:27], 7, v[10:11]
	v_lshl_or_b32 v26, v130, 2, v26
	v_lshl_add_u64 v[28:29], s[6:7], 0, v[26:27]
	v_lshl_add_u64 v[26:27], s[8:9], 0, v[26:27]
	s_waitcnt vmcnt(8)
	v_mov_b32_e32 v28, v242
	s_nop 0
	v_mov_b32_e32 v26, v243
	v_pk_mul_f32 v[30:31], v[14:15], v[28:29] op_sel_hi:[1,0]
	v_pk_mul_f32 v[26:27], v[14:15], v[26:27] op_sel:[1,0] op_sel_hi:[0,0]
	v_pk_fma_f32 v[14:15], v[14:15], v[28:29], v[26:27] op_sel_hi:[1,0,1] neg_lo:[0,0,1] neg_hi:[0,0,1]
	s_nop 0
	v_add_f32_e32 v14, v30, v26
.LBB0_1148:
	s_or_b64 exec, exec, s[48:49]
	v_cvt_pk_bf16_f32 v15, v15, s0
	v_cvt_pk_bf16_f32 v14, v14, s0
	v_mov_b32_e32 v19, v18
	ds_write_b16 v226, v15
	ds_write_b16 v227, v14 offset:64
	v_mov_b32_e32 v14, v0
	v_mov_b32_e32 v15, v4
	v_pk_mul_f32 v[14:15], v[14:15], v[18:19]
	s_and_saveexec_b64 s[48:49], vcc
	s_cbranch_execz .LBB0_1150
	v_lshlrev_b64 v[16:17], 7, v[16:17]
	v_lshl_or_b32 v16, v132, 2, v16
	v_lshl_add_u64 v[18:19], s[6:7], 0, v[16:17]
	v_lshl_add_u64 v[16:17], s[8:9], 0, v[16:17]
	s_waitcnt vmcnt(6)
	v_mov_b32_e32 v0, v244
	v_mov_b32_e32 v4, v245
	v_pk_mul_f32 v[16:17], v[14:15], v[0:1] op_sel_hi:[1,0]
	v_pk_mul_f32 v[18:19], v[14:15], v[4:5] op_sel:[1,0] op_sel_hi:[0,0]
	v_pk_fma_f32 v[14:15], v[14:15], v[0:1], v[18:19] op_sel_hi:[1,0,1] neg_lo:[0,0,1] neg_hi:[0,0,1]
	s_nop 0
	v_add_f32_e32 v14, v16, v18
.LBB0_1150:
	s_or_b64 exec, exec, s[48:49]
	v_cvt_pk_bf16_f32 v0, v15, s0
	v_mov_b32_e32 v21, v20
	ds_write_b16 v217, v0 offset:32
	v_cvt_pk_bf16_f32 v0, v14, s0
	v_mov_b32_e32 v4, v1
	ds_write_b16 v218, v0 offset:96
	v_pk_mul_f32 v[0:1], v[4:5], v[20:21]
	s_and_saveexec_b64 s[48:49], vcc
	s_cbranch_execz .LBB0_1152
	v_lshlrev_b64 v[4:5], 7, v[8:9]
	v_lshl_or_b32 v4, v132, 2, v4
	v_lshl_add_u64 v[8:9], s[6:7], 0, v[4:5]
	v_lshl_add_u64 v[4:5], s[8:9], 0, v[4:5]
	s_waitcnt vmcnt(4)
	v_mov_b32_e32 v8, v246
	s_nop 0
	v_mov_b32_e32 v4, v247
	v_pk_mul_f32 v[14:15], v[0:1], v[8:9] op_sel_hi:[1,0]
	v_pk_mul_f32 v[4:5], v[0:1], v[4:5] op_sel:[1,0] op_sel_hi:[0,0]
	v_pk_fma_f32 v[0:1], v[0:1], v[8:9], v[4:5] op_sel_hi:[1,0,1] neg_lo:[0,0,1] neg_hi:[0,0,1]
	s_nop 0
	v_add_f32_e32 v0, v14, v4
.LBB0_1152:
	s_or_b64 exec, exec, s[48:49]
	v_cvt_pk_bf16_f32 v1, v1, s0
	v_cvt_pk_bf16_f32 v0, v0, s0
	v_mov_b32_e32 v23, v22
	ds_write_b16 v220, v1 offset:32
	ds_write_b16 v221, v0 offset:96
	v_mov_b32_e32 v0, v2
	v_mov_b32_e32 v1, v6
	v_pk_mul_f32 v[0:1], v[0:1], v[22:23]
	s_and_saveexec_b64 s[48:49], vcc
	s_cbranch_execz .LBB0_1154
	v_lshlrev_b64 v[4:5], 7, v[12:13]
	v_lshl_or_b32 v4, v132, 2, v4
	v_lshl_add_u64 v[8:9], s[6:7], 0, v[4:5]
	v_lshl_add_u64 v[4:5], s[8:9], 0, v[4:5]
	s_waitcnt vmcnt(2)
	v_mov_b32_e32 v2, v248
	s_nop 0
	v_mov_b32_e32 v4, v249
	v_pk_mul_f32 v[8:9], v[0:1], v[2:3] op_sel_hi:[1,0]
	v_pk_mul_f32 v[4:5], v[0:1], v[4:5] op_sel:[1,0] op_sel_hi:[0,0]
	v_pk_fma_f32 v[0:1], v[0:1], v[2:3], v[4:5] op_sel_hi:[1,0,1] neg_lo:[0,0,1] neg_hi:[0,0,1]
	s_nop 0
	v_add_f32_e32 v0, v8, v4
.LBB0_1154:
	s_or_b64 exec, exec, s[48:49]
	v_mov_b32_e32 v25, v24
	v_cvt_pk_bf16_f32 v1, v1, s0
	v_cvt_pk_bf16_f32 v0, v0, s0
	v_mov_b32_e32 v6, v3
	ds_write_b16 v223, v1 offset:32
	ds_write_b16 v224, v0 offset:96
	v_pk_mul_f32 v[0:1], v[6:7], v[24:25]
	s_and_saveexec_b64 s[48:49], vcc
	s_cbranch_execz .LBB0_1156
	v_lshlrev_b64 v[2:3], 7, v[10:11]
	v_lshl_or_b32 v2, v132, 2, v2
	v_lshl_add_u64 v[4:5], s[6:7], 0, v[2:3]
	v_lshl_add_u64 v[2:3], s[8:9], 0, v[2:3]
	s_waitcnt vmcnt(0)
	v_mov_b32_e32 v4, v236
	s_nop 0
	v_mov_b32_e32 v2, v237
	v_pk_mul_f32 v[6:7], v[0:1], v[4:5] op_sel_hi:[1,0]
	v_pk_mul_f32 v[2:3], v[0:1], v[2:3] op_sel:[1,0] op_sel_hi:[0,0]
	v_pk_fma_f32 v[0:1], v[0:1], v[4:5], v[2:3] op_sel_hi:[1,0,1] neg_lo:[0,0,1] neg_hi:[0,0,1]
	s_nop 0
	v_add_f32_e32 v0, v6, v2

.LBB0_1395:
	s_ashr_i32 s4, s17, 31
	s_lshr_b32 s4, s4, 29
	s_add_i32 s4, s17, s4
	s_ashr_i32 s12, s4, 3
	s_lshl_b32 s18, s12, 6
	v_or_b32_e32 v0, s18, v16
	v_lshl_add_u32 v1, s12, 5, v17
	v_add_u32_e32 v2, 0xfffff800, v0
	v_cmp_gt_i32_e32 vcc, s16, v0
	s_mul_i32 s8, s12, 0xffa00000
	v_add_u32_e32 v6, s8, v25
	v_cndmask_b32_e32 v10, v2, v1, vcc
	v_cmp_lt_i32_e64 s[4:5], -1, v10
	v_lshl_add_u64 v[4:5], v[10:11], 2, s[52:53]
	v_mov_b32_e32 v10, v11
	v_mov_b64_e32 v[0:1], v[10:11]
	v_mov_b64_e32 v[2:3], v[10:11]
	s_waitcnt vmcnt(63) expcnt(7) lgkmcnt(15)
	s_barrier
	s_and_saveexec_b64 s[8:9], s[4:5]
	s_cbranch_execz .LBB0_1397
	v_ashrrev_i32_e32 v7, 31, v6
	v_lshl_add_u64 v[0:1], v[6:7], 2, v[4:5]
	global_load_dwordx4 v[0:3], v[0:1], off
	v_add_u32_e32 v56, 0x30000, v6
	v_ashrrev_i32_e32 v57, 31, v56
	v_lshl_add_u64 v[56:57], v[56:57], 2, v[4:5]
	global_load_dwordx4 v[40:43], v[56:57], off
	v_add_u32_e32 v56, 0x60000, v6
	v_ashrrev_i32_e32 v57, 31, v56
	v_lshl_add_u64 v[56:57], v[56:57], 2, v[4:5]
	global_load_dwordx4 v[44:47], v[56:57], off
	v_add_u32_e32 v56, 0x90000, v6
	v_ashrrev_i32_e32 v57, 31, v56
	v_lshl_add_u64 v[56:57], v[56:57], 2, v[4:5]
	global_load_dwordx4 v[48:51], v[56:57], off
.LBB0_1397:
	s_or_b64 exec, exec, s[8:9]
	s_lshl_b32 s8, s12, 10
	s_and_b64 vcc, exec, s[0:1]
	s_sub_i32 s12, 0, s8
	s_cbranch_vccnz .LBB0_1399
	s_add_i32 s8, s12, s3
	v_add_u32_e32 v26, s8, v8
	v_ashrrev_i32_e32 v27, 31, v26
	v_lshl_add_u64 v[26:27], v[26:27], 2, s[50:51]
	global_load_dword v10, v[26:27], off
	global_load_dword v52, v[26:27], off offset:128
	global_load_dword v53, v[26:27], off offset:256
	global_load_dword v54, v[26:27], off offset:384
	s_waitcnt vmcnt(0)
	v_pk_mul_f32 v[0:1], v[0:1], v[10:11] op_sel_hi:[1,0]
	v_pk_mul_f32 v[2:3], v[2:3], v[10:11] op_sel_hi:[1,0]
.LBB0_1399:
	v_mov_b32_e32 v10, v11
	s_waitcnt vmcnt(0)
	ds_write_b128 v19, v[0:3]
	v_mov_b64_e32 v[0:1], v[10:11]
	v_mov_b64_e32 v[2:3], v[10:11]
	s_and_saveexec_b64 s[8:9], s[4:5]
	s_cbranch_execz .LBB0_1401
	v_mov_b64_e32 v[0:1], v[40:41]
	v_mov_b64_e32 v[2:3], v[42:43]
.LBB0_1401:
	s_or_b64 exec, exec, s[8:9]
	s_and_b64 vcc, exec, s[0:1]
	s_add_i32 s8, s3, s12
	s_cbranch_vccnz .LBB0_1403
	s_ashr_i32 s9, s8, 31
	v_lshl_add_u64 v[26:27], s[8:9], 0, v[8:9]
	v_lshl_add_u64 v[26:27], v[26:27], 2, s[50:51]
	v_mov_b32_e32 v10, v52
	s_waitcnt vmcnt(0)
	v_pk_mul_f32 v[0:1], v[0:1], v[10:11] op_sel_hi:[1,0]
	v_pk_mul_f32 v[2:3], v[2:3], v[10:11] op_sel_hi:[1,0]
.LBB0_1403:
	v_mov_b32_e32 v10, v11
	s_waitcnt vmcnt(0)
	ds_write_b128 v21, v[0:3]
	v_mov_b64_e32 v[0:1], v[10:11]
	v_mov_b64_e32 v[2:3], v[10:11]
	s_and_saveexec_b64 s[12:13], s[4:5]
	s_cbranch_execz .LBB0_1405
	v_mov_b64_e32 v[0:1], v[44:45]
	v_mov_b64_e32 v[2:3], v[46:47]
.LBB0_1405:
	s_or_b64 exec, exec, s[12:13]
	s_and_b64 vcc, exec, s[0:1]
	s_cbranch_vccnz .LBB0_1407
	s_ashr_i32 s9, s8, 31
	v_lshl_add_u64 v[26:27], s[8:9], 0, v[8:9]
	v_lshl_add_u64 v[26:27], v[26:27], 2, s[50:51]
	v_mov_b32_e32 v10, v53
	s_waitcnt vmcnt(0)
	v_pk_mul_f32 v[0:1], v[0:1], v[10:11] op_sel_hi:[1,0]
	v_pk_mul_f32 v[2:3], v[2:3], v[10:11] op_sel_hi:[1,0]
.LBB0_1407:
	v_mov_b32_e32 v10, v11
	s_waitcnt vmcnt(0)
	ds_write_b128 v22, v[0:3]
	v_mov_b64_e32 v[0:1], v[10:11]
	v_mov_b64_e32 v[2:3], v[10:11]
	s_and_saveexec_b64 s[12:13], s[4:5]
	s_cbranch_execz .LBB0_1409
	v_mov_b64_e32 v[0:1], v[48:49]
	v_mov_b64_e32 v[2:3], v[50:51]
.LBB0_1409:
	s_or_b64 exec, exec, s[12:13]
	s_and_b64 vcc, exec, s[6:7]
	s_cbranch_vccz .LBB0_1411
	s_ashr_i32 s9, s8, 31
	v_lshl_add_u64 v[4:5], s[8:9], 0, v[8:9]
	v_lshl_add_u64 v[4:5], v[4:5], 2, s[50:51]
	v_mov_b32_e32 v6, v54
	s_waitcnt vmcnt(0)
	v_pk_mul_f32 v[4:5], v[0:1], v[6:7] op_sel_hi:[1,0]
	v_pk_mul_f32 v[6:7], v[2:3], v[6:7] op_sel_hi:[1,0]
	s_cbranch_execnz .LBB0_1394
	s_branch .LBB0_1412
